# pvprio_s with the PV priority raise started before the P-pack conversions (covers cvt_pk + PV MFMAs)
# speedup vs baseline: 1.0035x; 1.0035x over previous
; template <int MODE> ...
;     ...
;             bf16x8 kf[2][2][2];
; #pragma unroll
;             for (int jj = 0; jj < 2; ++jj)
; #pragma unroll
;                 for (int kt = 0; kt < 2; ++kt)
; #pragma unroll
;                     for (int ks = 0; ks < 2; ++ks) kf[jj][kt][ks] = *(const LAS bf16x8*)(Sl + kad[jj][ks] + (32 * hf + 16 * kt) * 128);
;             f32x4 bb[2][2];
; #pragma unroll
;             for (int jj = 0; jj < 2; ++jj) { const LAS f32x4* bl = bcp + ((MODE == 0) ? (dr0 + t - act0) * 8 : 16 * t + 8 * hf) + bofs[jj];
; #pragma unroll
;                 for (int kt = 0; kt < 2; ++kt) bb[jj][kt] = bl[4 * kt]; }
;             s16x4 vlo[2][4], vhi[2][4];
; #pragma unroll
;             for (int jj = 0; jj < 2; ++jj)
; #pragma unroll
;                 for (int dt = 0; dt < 4; ++dt) { const LAS unsigned char* vp = Sl + vad[jj] + (32 * hf) * 128 + ((dt ^ sv) << 5);
;                     vlo[jj][dt] = __builtin_bit_cast(s16x4, __builtin_amdgcn_ds_read_tr16_b64_v4i16((LAS s16x4*)(vp)));
;                     vhi[jj][dt] = __builtin_bit_cast(s16x4, __builtin_amdgcn_ds_read_tr16_b64_v4i16((LAS s16x4*)(vp + 2048))); }
;             __builtin_amdgcn_sched_barrier(0);
;             f32x4 s[2][2];
; #pragma unroll
;             for (int jj = 0; jj < 2; ++jj)
; #pragma unroll
;                 for (int kt = 0; kt < 2; ++kt) { f32x4 a = (MODE == 0) ? bb[jj][kt] + mneg[jj][kt] : bb[jj][kt];
;                     a = __builtin_amdgcn_mfma_f32_16x16x32_bf16(kf[jj][kt][0], qf[jj][0], a, 0, 0, 0);
;                     s[jj][kt] = __builtin_amdgcn_mfma_f32_16x16x32_bf16(kf[jj][kt][1], qf[jj][1], a, 0, 0, 0); }
;             u32x4 pw[2];
; #pragma unroll
;             for (int jj = 0; jj < 2; ++jj) {
;                 const float tm = vmax3(vmax3(s[jj][0][0], s[jj][0][1], s[jj][0][2]), vmax3(s[jj][0][3], s[jj][1][0], s[jj][1][1]), vmax3(s[jj][1][2], s[jj][1][3], s[jj][1][3]));
;                 const float mn = quad_max3(mrun[jj], tm);
;                 const float alpha = __builtin_amdgcn_exp2f(mrun[jj] - mn);
;                 mrun[jj] = mn;
;                 float rsum = 0.f;
; #pragma unroll
;                 for (int kt = 0; kt < 2; ++kt)
; #pragma unroll
;                     for (int e = 0; e < 4; ++e) { s[jj][kt][e] = __builtin_amdgcn_exp2f(s[jj][kt][e] - mn); rsum += s[jj][kt][e]; }
;                 lrun[jj] = lrun[jj] * alpha + rsum;
; #pragma unroll
.LBB0_278:
	s_sub_i32 s52, s25, s23
	v_lshlrev_b32_e32 v94, 5, v93
	s_add_i32 s0, s23, 7
	v_xor_b32_e32 v95, 32, v94
	v_xor_b32_e32 v96, 64, v94
	s_cmp_gt_u32 s0, 7
	v_xor_b32_e32 v97, 0x60, v94
	s_cbranch_scc1 .LBB0_291
	s_lshl_b32 s0, s86, 14
	s_add_i32 s0, s0, 0
	v_add_u32_e32 v0, s0, v89
	s_lshl_b32 s14, s52, 7
	v_add_u32_e32 v2, s0, v88
	ds_read_b128 v[6:9], v0
	ds_read_b128 v[10:13], v0 offset:2048
	ds_read_b128 v[14:17], v2
	ds_read_b128 v[34:37], v2 offset:2048
	v_add_u32_e32 v0, s0, v92
	s_add_i32 s14, s24, s14
	v_add_u32_e32 v2, s0, v91
	ds_read_b128 v[38:41], v0
	ds_read_b128 v[42:45], v0 offset:2048
	ds_read_b128 v[46:49], v2
	ds_read_b128 v[50:53], v2 offset:2048
	v_lshl_add_u32 v0, v87, 4, s14
	ds_read_b128 v[54:57], v0
	ds_read_b128 v[58:61], v0 offset:64
	v_lshl_add_u32 v0, v90, 4, s14
	ds_read_b128 v[62:65], v0
	ds_read_b128 v[66:69], v0 offset:64
	v_add3_u32 v0, v86, v122, s0
	v_add_u32_e32 v2, v0, v94
	v_add_u32_e32 v3, v0, v95
	ds_read_b64_tr_b16 v[70:71], v2 offset:8192
	ds_read_b64_tr_b16 v[72:73], v2 offset:10240
	ds_read_b64_tr_b16 v[74:75], v3 offset:8192
	ds_read_b64_tr_b16 v[76:77], v3 offset:10240
	v_add_u32_e32 v2, v0, v96
	v_add_u32_e32 v0, v0, v97
	ds_read_b64_tr_b16 v[78:79], v2 offset:8192
	ds_read_b64_tr_b16 v[80:81], v2 offset:10240
	ds_read_b64_tr_b16 v[126:127], v0 offset:8192
	ds_read_b64_tr_b16 v[128:129], v0 offset:10240
	v_add3_u32 v0, v123, v122, s0
	v_add_u32_e32 v2, v0, v94
	v_add_u32_e32 v3, v0, v95
	ds_read_b64_tr_b16 v[130:131], v2 offset:8192
	ds_read_b64_tr_b16 v[132:133], v2 offset:10240
	ds_read_b64_tr_b16 v[134:135], v3 offset:8192
	ds_read_b64_tr_b16 v[136:137], v3 offset:10240
	v_add_u32_e32 v2, v0, v96
	v_add_u32_e32 v0, v0, v97
	ds_read_b64_tr_b16 v[138:139], v2 offset:8192
	ds_read_b64_tr_b16 v[140:141], v2 offset:10240
	ds_read_b64_tr_b16 v[2:3], v0 offset:8192
	ds_read_b64_tr_b16 v[4:5], v0 offset:10240
	s_waitcnt lgkmcnt(14)
	v_pk_add_f32 v[56:57], v[112:113], v[56:57]
	v_pk_add_f32 v[54:55], v[110:111], v[54:55]
	s_mov_b32 s0, 0xf149f2ca
	s_nop 0
	v_mfma_f32_16x16x32_bf16 v[6:9], v[6:9], v[30:33], v[54:57]
	s_nop 2
	v_pk_add_f32 v[56:57], v[114:115], v[60:61]
	v_pk_add_f32 v[54:55], v[108:109], v[58:59]
	v_mfma_f32_16x16x32_bf16 v[6:9], v[14:17], v[26:29], v[6:9]
	v_pk_add_f32 v[16:17], v[106:107], v[64:65]
	v_pk_add_f32 v[14:15], v[102:103], v[62:63]
	v_mfma_f32_16x16x32_bf16 v[10:13], v[10:13], v[30:33], v[54:57]
	v_mfma_f32_16x16x32_bf16 v[10:13], v[34:37], v[26:29], v[10:13]
	s_nop 2
	v_maximum3_f32 v0, v6, v7, v8
	v_pk_add_f32 v[56:57], v[104:105], v[68:69]
	v_pk_add_f32 v[54:55], v[100:101], v[66:67]
	v_mfma_f32_16x16x32_bf16 v[14:17], v[38:41], v[22:25], v[14:17]
	v_mfma_f32_16x16x32_bf16 v[14:17], v[46:49], v[18:21], v[14:17]
	v_maximum3_f32 v34, v9, v10, v11
	v_maximum3_f32 v35, v12, v13, v13
	v_maximum3_f32 v0, v0, v34, v35
	v_mov_b32_e32 v34, v0
	s_nop 1
	v_permlane16_swap_b32_e32 v0, v34
	v_maximum3_f32 v0, v0, v34, v34
	v_mov_b32_e32 v34, v0
	s_nop 1
	v_permlane32_swap_b32_e32 v0, v34
	v_maximum3_f32 v125, v0, s0, v34
	v_mfma_f32_16x16x32_bf16 v[34:37], v[42:45], v[22:25], v[54:57]
	v_pk_add_f32 v[200:201], v[6:7], v[124:125] op_sel:[0,1] op_sel_hi:[1,1] neg_lo:[0,1] neg_hi:[0,1]
	v_pk_add_f32 v[202:203], v[8:9], v[124:125] op_sel:[0,1] op_sel_hi:[1,1] neg_lo:[0,1] neg_hi:[0,1]
	v_pk_add_f32 v[204:205], v[10:11], v[124:125] op_sel:[0,1] op_sel_hi:[1,1] neg_lo:[0,1] neg_hi:[0,1]
	v_pk_add_f32 v[206:207], v[12:13], v[124:125] op_sel:[0,1] op_sel_hi:[1,1] neg_lo:[0,1] neg_hi:[0,1]
	v_exp_f32_e32 v38, v200
	v_mfma_f32_16x16x32_bf16 v[34:37], v[50:53], v[18:21], v[34:37]
	v_exp_f32_e32 v40, v201
	v_exp_f32_e32 v42, v202
	v_sub_f32_e32 v0, 0xf149f2ca, v125
	v_exp_f32_e32 v66, v203
	v_exp_f32_e32 v68, v204
	v_exp_f32_e32 v146, v0
	v_maximum3_f32 v0, v14, v15, v16
	v_maximum3_f32 v10, v17, v34, v35
	v_maximum3_f32 v11, v36, v37, v37
	v_maximum3_f32 v0, v0, v10, v11
	v_mov_b32_e32 v10, v0
	s_nop 1
	v_permlane16_swap_b32_e32 v0, v10
	v_maximum3_f32 v0, v0, v10, v10
	v_mov_b32_e32 v10, v0
	s_nop 1
	v_permlane32_swap_b32_e32 v0, v10
	v_maximum3_f32 v124, v0, s0, v10
	v_exp_f32_e32 v98, v205
	v_sub_f32_e32 v0, 0xf149f2ca, v124
	v_exp_f32_e32 v142, v206
	v_pk_add_f32 v[208:209], v[14:15], v[124:125] op_sel_hi:[1,0] neg_lo:[0,1] neg_hi:[0,1]
	v_pk_add_f32 v[210:211], v[16:17], v[124:125] op_sel_hi:[1,0] neg_lo:[0,1] neg_hi:[0,1]
	v_pk_add_f32 v[212:213], v[34:35], v[124:125] op_sel_hi:[1,0] neg_lo:[0,1] neg_hi:[0,1]
	v_pk_add_f32 v[214:215], v[36:37], v[124:125] op_sel_hi:[1,0] neg_lo:[0,1] neg_hi:[0,1]
	v_exp_f32_e32 v147, v0
	v_exp_f32_e32 v144, v207
	v_exp_f32_e32 v39, v208
	v_exp_f32_e32 v41, v209
	v_exp_f32_e32 v43, v210
	v_exp_f32_e32 v69, v212
	v_exp_f32_e32 v67, v211
	v_pk_mul_f32 v[10:11], v[146:147], 0 op_sel_hi:[1,0]
	v_exp_f32_e32 v99, v213
	v_cvt_pk_bf16_f32 v6, v38, v40
	v_cvt_pk_bf16_f32 v7, v42, v66
	v_cvt_pk_bf16_f32 v8, v68, v98
	v_cvt_pk_bf16_f32 v9, v142, v144
	v_mov_b32_e32 v14, v10
	v_mov_b32_e32 v15, v10
	v_mov_b32_e32 v16, v10
	v_mov_b32_e32 v17, v10
	v_exp_f32_e32 v143, v214
	v_mfma_f32_16x16x32_bf16 v[54:57], v[70:73], v[6:9], v[14:17]
	v_exp_f32_e32 v145, v215
	s_setprio 1
	v_mov_b32_e32 v10, v11
	v_mov_b32_e32 v12, v11
	s_waitcnt lgkmcnt(12)
	v_mfma_f32_16x16x32_bf16 v[62:65], v[74:77], v[6:9], v[14:17]
	v_mov_b32_e32 v13, v11
	v_cvt_pk_bf16_f32 v34, v39, v41
	v_cvt_pk_bf16_f32 v35, v43, v67
	s_waitcnt lgkmcnt(10)
	v_mfma_f32_16x16x32_bf16 v[58:61], v[78:81], v[6:9], v[14:17]
	v_cvt_pk_bf16_f32 v36, v69, v99
	v_cvt_pk_bf16_f32 v37, v143, v145
	s_waitcnt lgkmcnt(8)
	v_mfma_f32_16x16x32_bf16 v[50:53], v[126:129], v[6:9], v[14:17]
	v_add_f32_e64 v6, v38, 0
	v_add_f32_e64 v7, v39, 0
	v_pk_add_f32 v[6:7], v[40:41], v[6:7]
	s_waitcnt lgkmcnt(6)
	v_mfma_f32_16x16x32_bf16 v[46:49], v[130:133], v[34:37], v[10:13]
	v_pk_add_f32 v[6:7], v[42:43], v[6:7]
	v_pk_add_f32 v[6:7], v[66:67], v[6:7]
	s_waitcnt lgkmcnt(4)
	v_mfma_f32_16x16x32_bf16 v[42:45], v[134:137], v[34:37], v[10:13]
	v_pk_add_f32 v[6:7], v[68:69], v[6:7]
	v_pk_add_f32 v[6:7], v[98:99], v[6:7]
	s_waitcnt lgkmcnt(2)
	v_mfma_f32_16x16x32_bf16 v[38:41], v[138:141], v[34:37], v[10:13]
	v_pk_add_f32 v[6:7], v[142:143], v[6:7]
	v_pk_add_f32 v[6:7], v[144:145], v[6:7]
	s_waitcnt lgkmcnt(0)
	v_mfma_f32_16x16x32_bf16 v[34:37], v[2:5], v[34:37], v[10:13]
	s_setprio 0
	v_fma_f32 v98, v146, 0, v6
	v_fma_f32 v99, v147, 0, v7
	s_cmp_eq_u32 s41, 1
	s_cbranch_scc1 .LBB0_281
	s_branch .LBB0_292

; #define LAS __attribute__((address_space(3)))
; #define GAS __attribute__((address_space(1)))
; template <int MODE> ...
;     ...
;     auto head = [&](const int t) __attribute__((always_inline)) {
;         if (t >= 2) { if (t + 1 < nT || nK) asm volatile("s_waitcnt vmcnt(2)" ::: "memory"); else asm volatile("s_waitcnt vmcnt(0)" ::: "memory"); }
;         __builtin_amdgcn_s_barrier();
;         if (t + 2 < nT) DMA_TILE(t + 2); else if (nK) DMA_NEXT(t + 2 - nT);
;     };
;     auto body = [&](const int t) __attribute__((always_inline)) {
;         if (t >= act0 && t < act0 + actn) {
;         const LAS unsigned char* Sl = ring + ((t + base) % 3) * SLOT;
; #pragma unroll
;         for (int hf = 0; hf < NH; ++hf) {
;             if (MODE == 1) { const int ks = ktok0 + 64 * t + 32 * hf;
;                 if (ks + 31 < qtok0 - 128 || ks > qtok0 + 31 + 128) continue; }
;             bf16x8 kf[2][2][2];
; #pragma unroll
;             for (int jj = 0; jj < 2; ++jj)
; #pragma unroll
;                 for (int kt = 0; kt < 2; ++kt)
; #pragma unroll
;                     for (int ks = 0; ks < 2; ++ks) kf[jj][kt][ks] = *(const LAS bf16x8*)(Sl + kad[jj][ks] + (32 * hf + 16 * kt) * 128);
;             f32x4 bb[2][2];
; #pragma unroll
;             for (int jj = 0; jj < 2; ++jj) { const LAS f32x4* bl = bcp + ((MODE == 0) ? (dr0 + t - act0) * 8 : 16 * t + 8 * hf) + bofs[jj];
; #pragma unroll
;                 for (int kt = 0; kt < 2; ++kt) bb[jj][kt] = bl[4 * kt]; }
;             s16x4 vlo[2][4], vhi[2][4];
; #pragma unroll
;             for (int jj = 0; jj < 2; ++jj)
; #pragma unroll
;                 for (int dt = 0; dt < 4; ++dt) { const LAS unsigned char* vp = Sl + vad[jj] + (32 * hf) * 128 + ((dt ^ sv) << 5);
;                     vlo[jj][dt] = __builtin_bit_cast(s16x4, __builtin_amdgcn_ds_read_tr16_b64_v4i16((LAS s16x4*)(vp)));
;                     vhi[jj][dt] = __builtin_bit_cast(s16x4, __builtin_amdgcn_ds_read_tr16_b64_v4i16((LAS s16x4*)(vp + 2048))); }
;     ...
;     bf16x8 qn[2][2];
;     { const GAS bf16_t* qs = nQ ? (const GAS bf16_t*)nQ : (const GAS bf16_t*)proj + (size_t)qtok0 * NIN + qcol;
; #pragma unroll
;       for (int jj = 0; jj < 2; ++jj)
; #pragma unroll
;           for (int ks = 0; ks < 2; ++ks) qn[jj][ks] = *(const GAS bf16x8*)(qs + (size_t)(16 * jj) * NIN + 32 * ks + qoff); }
.LBB0_283:
	s_add_i32 s42, s86, s26
	s_add_i32 s0, s42, 1
	s_mul_hi_i32 s14, s0, 0x55555556
	s_lshr_b32 s15, s14, 31
	s_add_i32 s14, s14, s15
	s_mul_i32 s14, s14, 3
	s_sub_i32 s0, s0, s14
	s_lshl_b32 s0, s0, 14
	s_add_i32 s0, s0, s94
	s_add_u32 s34, s34, 0x48000
	s_addc_u32 s35, s35, 0
	s_add_u32 s30, s30, 0x48000
	s_barrier
	s_addc_u32 s31, s31, 0
	s_mov_b32 m0, s0
	s_nop 0
	global_load_lds_dwordx4 v84, s[34:35]
	s_add_u32 m0, m0, 0x2000
	s_nop 0
	global_load_lds_dwordx4 v85, s[30:31]
	v_lshl_add_u64 v[6:7], v[82:83], 1, s[38:39]
	global_load_dwordx4 v[2:5], v[6:7], off
	global_load_dwordx4 v[10:13], v[6:7], off offset:64
	v_add_co_u32_e32 v6, vcc, 0x12000, v6
	s_cmp_gt_u32 s40, s27
	s_nop 0
	v_addc_co_u32_e32 v7, vcc, 0, v7, vcc
	global_load_dwordx4 v[14:17], v[6:7], off
	s_nop 0
	global_load_dwordx4 v[6:9], v[6:7], off offset:64
	s_cselect_b64 s[30:31], -1, 0
	s_add_i32 s0, s23, 8
	s_cmp_le_i32 s26, s0
	s_cselect_b64 s[26:27], -1, 0
	s_and_b64 s[26:27], s[30:31], s[26:27]
	s_and_b64 vcc, exec, s[26:27]
	s_cbranch_vccz .LBB0_285
	s_add_i32 s0, s41, s86
	s_mul_hi_i32 s14, s0, 0x55555556
	s_lshr_b32 s15, s14, 31
	s_add_i32 s14, s14, s15
	s_mul_i32 s14, s14, 3
	s_sub_i32 s0, s0, s14
	s_lshl_b32 s0, s0, 14
	s_sub_i32 s14, s41, s23
	s_add_i32 s0, s0, 0
	s_add_i32 s14, s14, s25
	v_add_u32_e32 v0, s0, v89
	s_lshl_b32 s14, s14, 7
	v_add_u32_e32 v66, s0, v88
	ds_read_b128 v[126:129], v0
	ds_read_b128 v[130:133], v0 offset:2048
	ds_read_b128 v[134:137], v66
	ds_read_b128 v[138:141], v66 offset:2048
	v_add_u32_e32 v0, s0, v92
	s_add_i32 s24, s24, s14
	v_add_u32_e32 v66, s0, v91
	ds_read_b128 v[142:145], v0
	ds_read_b128 v[146:149], v0 offset:2048
	ds_read_b128 v[150:153], v66
	ds_read_b128 v[154:157], v66 offset:2048
	v_lshl_add_u32 v0, v87, 4, s24
	ds_read_b128 v[158:161], v0
	ds_read_b128 v[162:165], v0 offset:64
	v_lshl_add_u32 v0, v90, 4, s24
	ds_read_b128 v[166:169], v0
	ds_read_b128 v[170:173], v0 offset:64
	v_lshlrev_b32_e32 v0, 5, v93
	v_add3_u32 v66, v86, v122, s0
	v_add_u32_e32 v67, v66, v0
	v_xor_b32_e32 v68, 32, v0
	v_add_u32_e32 v69, v66, v68
	ds_read_b64_tr_b16 v[94:95], v67 offset:8192
	ds_read_b64_tr_b16 v[96:97], v67 offset:10240
	ds_read_b64_tr_b16 v[90:91], v69 offset:8192
	ds_read_b64_tr_b16 v[92:93], v69 offset:10240
	v_xor_b32_e32 v67, 64, v0
	v_xor_b32_e32 v70, 0x60, v0
	v_add_u32_e32 v69, v66, v67
	v_add_u32_e32 v66, v66, v70
	ds_read_b64_tr_b16 v[86:87], v69 offset:8192
	ds_read_b64_tr_b16 v[88:89], v69 offset:10240
	ds_read_b64_tr_b16 v[82:83], v66 offset:8192
	ds_read_b64_tr_b16 v[84:85], v66 offset:10240
	v_add3_u32 v66, v123, v122, s0
	v_add_u32_e32 v0, v66, v0
	v_add_u32_e32 v68, v66, v68
	ds_read_b64_tr_b16 v[78:79], v0 offset:8192
	ds_read_b64_tr_b16 v[80:81], v0 offset:10240
	ds_read_b64_tr_b16 v[74:75], v68 offset:8192
	ds_read_b64_tr_b16 v[76:77], v68 offset:10240
	v_add_u32_e32 v0, v66, v67
	v_add_u32_e32 v68, v66, v70
	ds_read_b64_tr_b16 v[70:71], v0 offset:8192
	ds_read_b64_tr_b16 v[72:73], v0 offset:10240
	ds_read_b64_tr_b16 v[66:67], v68 offset:8192
	ds_read_b64_tr_b16 v[68:69], v68 offset:10240
	s_waitcnt lgkmcnt(14)
; __device__ __forceinline__ unsigned cvtpk(float lo, float hi) { f32x2 v = {lo, hi}; bf16x2_t b = __builtin_convertvector(v, bf16x2_t); return __builtin_bit_cast(unsigned, b); }
; __device__ __forceinline__ float vmax3(float a, float b, float c) { return __builtin_elementwise_maximum(__builtin_elementwise_maximum(a, b), c); }
; template <int MODE> ...
;     ...
;             f32x4 s[2][2];
; #pragma unroll
;             for (int jj = 0; jj < 2; ++jj)
; #pragma unroll
;                 for (int kt = 0; kt < 2; ++kt) { f32x4 a = (MODE == 0) ? bb[jj][kt] + mneg[jj][kt] : bb[jj][kt];
;                     a = __builtin_amdgcn_mfma_f32_16x16x32_bf16(kf[jj][kt][0], qf[jj][0], a, 0, 0, 0);
;                     s[jj][kt] = __builtin_amdgcn_mfma_f32_16x16x32_bf16(kf[jj][kt][1], qf[jj][1], a, 0, 0, 0); }
;             u32x4 pw[2];
; #pragma unroll
;             for (int jj = 0; jj < 2; ++jj) {
;                 const float tm = vmax3(vmax3(s[jj][0][0], s[jj][0][1], s[jj][0][2]), vmax3(s[jj][0][3], s[jj][1][0], s[jj][1][1]), vmax3(s[jj][1][2], s[jj][1][3], s[jj][1][3]));
;                 const float mn = quad_max3(mrun[jj], tm);
;                 const float alpha = __builtin_amdgcn_exp2f(mrun[jj] - mn);
;                 mrun[jj] = mn;
;                 float rsum = 0.f;
; #pragma unroll
;                 for (int kt = 0; kt < 2; ++kt)
; #pragma unroll
;                     for (int e = 0; e < 4; ++e) { s[jj][kt][e] = __builtin_amdgcn_exp2f(s[jj][kt][e] - mn); rsum += s[jj][kt][e]; }
;                 lrun[jj] = lrun[jj] * alpha + rsum;
; #pragma unroll
;                 for (int dt = 0; dt < 4; ++dt) o[jj][dt] *= alpha;
;                 pw[jj].x = cvtpk(s[jj][0][0], s[jj][0][1]); pw[jj].y = cvtpk(s[jj][0][2], s[jj][0][3]); pw[jj].z = cvtpk(s[jj][1][0], s[jj][1][1]); pw[jj].w = cvtpk(s[jj][1][2], s[jj][1][3]);
;             }
; #pragma unroll
;             for (int jj = 0; jj < 2; ++jj)
; #pragma unroll
;                 for (int dt = 0; dt < 4; ++dt) {
;                     const bf16x8 vf = (bf16x8){vlo[jj][dt][0], vlo[jj][dt][1], vlo[jj][dt][2], vlo[jj][dt][3], vhi[jj][dt][0], vhi[jj][dt][1], vhi[jj][dt][2], vhi[jj][dt][3]};
;                     o[jj][dt] = __builtin_amdgcn_mfma_f32_16x16x32_bf16(vf, __builtin_bit_cast(bf16x8, pw[jj]), o[jj][dt], 0, 0, 0); }
;             __builtin_amdgcn_sched_barrier(0);
	v_pk_add_f32 v[112:113], v[112:113], v[160:161]
	v_pk_add_f32 v[110:111], v[110:111], v[158:159]
	v_pk_add_f32 v[114:115], v[114:115], v[164:165]
	v_pk_add_f32 v[100:101], v[100:101], v[170:171]
	v_mfma_f32_16x16x32_bf16 v[110:113], v[126:129], v[30:33], v[110:113]
	v_mfma_f32_16x16x32_bf16 v[126:129], v[134:137], v[26:29], v[110:113]
	s_nop 6
	v_pk_add_f32 v[112:113], v[108:109], v[162:163]
	v_maximum3_f32 v0, v126, v127, v128
	v_pk_add_f32 v[108:109], v[106:107], v[168:169]
	v_mfma_f32_16x16x32_bf16 v[30:33], v[130:133], v[30:33], v[112:115]
	v_pk_add_f32 v[106:107], v[102:103], v[166:167]
	v_pk_add_f32 v[102:103], v[104:105], v[172:173]
	v_mfma_f32_16x16x32_bf16 v[26:29], v[138:141], v[26:29], v[30:33]
	s_nop 7
	v_maximum3_f32 v30, v129, v26, v27
	v_maximum3_f32 v31, v28, v29, v29
	v_maximum3_f32 v0, v0, v30, v31
	v_mov_b32_e32 v104, v0
	s_nop 1
	v_permlane16_swap_b32_e32 v0, v104
	v_mfma_f32_16x16x32_bf16 v[30:33], v[142:145], v[22:25], v[106:109]
	v_maximum3_f32 v0, v0, v104, v104
	v_mov_b32_e32 v104, v0
	s_nop 1
	v_permlane32_swap_b32_e32 v0, v104
	v_mfma_f32_16x16x32_bf16 v[22:25], v[146:149], v[22:25], v[100:103]
	v_maximum3_f32 v0, v125, v0, v104
	v_mfma_f32_16x16x32_bf16 v[30:33], v[150:153], v[18:21], v[30:33]
	s_nop 0
	v_sub_f32_e32 v100, v125, v0
	v_exp_f32_e32 v122, v100
	v_sub_f32_e32 v101, v126, v0
	v_mfma_f32_16x16x32_bf16 v[18:21], v[154:157], v[18:21], v[22:25]
	v_exp_f32_e32 v104, v101
	v_pk_mul_f32 v[60:61], v[60:61], v[122:123] op_sel_hi:[1,0]
	v_pk_mul_f32 v[58:59], v[58:59], v[122:123] op_sel_hi:[1,0]
	v_sub_f32_e32 v22, v127, v0
	v_exp_f32_e32 v106, v22
	v_sub_f32_e32 v22, v128, v0
	v_exp_f32_e32 v108, v22
	v_sub_f32_e32 v22, v129, v0
	v_exp_f32_e32 v110, v22
	v_sub_f32_e32 v22, v26, v0
	v_exp_f32_e32 v112, v22
	v_sub_f32_e32 v22, v27, v0
	v_exp_f32_e32 v114, v22
	v_sub_f32_e32 v22, v28, v0
	v_sub_f32_e32 v0, v29, v0
	v_exp_f32_e32 v126, v22
	v_exp_f32_e32 v128, v0
	v_pk_mul_f32 v[22:23], v[54:55], v[122:123] op_sel_hi:[1,0]
	v_maximum3_f32 v0, v30, v31, v32
	v_maximum3_f32 v54, v33, v18, v19
	v_maximum3_f32 v55, v20, v21, v21
	v_maximum3_f32 v0, v0, v54, v55
	v_mov_b32_e32 v54, v0
	s_nop 1
	v_permlane16_swap_b32_e32 v0, v54
	v_maximum3_f32 v0, v0, v54, v54
	v_mov_b32_e32 v54, v0
	s_nop 1
	v_permlane32_swap_b32_e32 v0, v54
	v_maximum3_f32 v0, v124, v0, v54
	v_sub_f32_e32 v30, v30, v0
	v_exp_f32_e32 v105, v30
	v_sub_f32_e32 v30, v31, v0
	v_exp_f32_e32 v107, v30
	v_sub_f32_e32 v30, v32, v0
	v_sub_f32_e32 v18, v18, v0
	v_exp_f32_e32 v109, v30
	v_sub_f32_e32 v30, v33, v0
	v_exp_f32_e32 v113, v18
	v_sub_f32_e32 v18, v19, v0
	v_sub_f32_e32 v54, v124, v0
	v_exp_f32_e32 v111, v30
	v_exp_f32_e32 v115, v18
	v_sub_f32_e32 v18, v20, v0
	v_pk_mul_f32 v[24:25], v[56:57], v[122:123] op_sel_hi:[1,0]
	v_pk_mul_f32 v[28:29], v[64:65], v[122:123] op_sel_hi:[1,0]
	v_pk_mul_f32 v[26:27], v[62:63], v[122:123] op_sel_hi:[1,0]
	v_pk_mul_f32 v[52:53], v[52:53], v[122:123] op_sel_hi:[1,0]
	v_pk_mul_f32 v[50:51], v[50:51], v[122:123] op_sel_hi:[1,0]
	v_exp_f32_e32 v127, v18
	v_sub_f32_e32 v0, v21, v0
	v_exp_f32_e32 v123, v54
	v_pk_add_f32 v[18:19], v[104:105], 0 op_sel_hi:[1,0]
	v_exp_f32_e32 v129, v0
	v_pk_add_f32 v[18:19], v[106:107], v[18:19]
	v_cvt_pk_bf16_f32 v100, v104, v106
	v_pk_add_f32 v[18:19], v[108:109], v[18:19]
	v_cvt_pk_bf16_f32 v101, v108, v110
	v_pk_add_f32 v[18:19], v[110:111], v[18:19]
	v_cvt_pk_bf16_f32 v102, v112, v114
	v_cvt_pk_bf16_f32 v103, v126, v128
	v_pk_add_f32 v[18:19], v[112:113], v[18:19]
	v_mov_b32_e32 v0, v123
	v_mfma_f32_16x16x32_bf16 v[54:57], v[94:97], v[100:103], v[22:25]
	s_setprio 1
	v_pk_mul_f32 v[20:21], v[48:49], v[0:1] op_sel_hi:[1,0]
	s_waitcnt lgkmcnt(12)
	v_mfma_f32_16x16x32_bf16 v[62:65], v[90:93], v[100:103], v[26:29]
	v_cvt_pk_bf16_f32 v22, v105, v107
	v_cvt_pk_bf16_f32 v23, v109, v111
	v_cvt_pk_bf16_f32 v24, v113, v115
	v_pk_add_f32 v[26:27], v[114:115], v[18:19]
	v_pk_mul_f32 v[18:19], v[46:47], v[0:1] op_sel_hi:[1,0]
	v_cvt_pk_bf16_f32 v25, v127, v129
	s_waitcnt lgkmcnt(10)
	v_mfma_f32_16x16x32_bf16 v[58:61], v[86:89], v[100:103], v[58:61]
	v_pk_add_f32 v[26:27], v[126:127], v[26:27]
	v_pk_add_f32 v[26:27], v[128:129], v[26:27]
	s_waitcnt lgkmcnt(6)
	v_mfma_f32_16x16x32_bf16 v[46:49], v[78:81], v[22:25], v[18:21]
	v_fma_f32 v98, v98, v122, v26
	v_fma_f32 v99, v99, v123, v27
	s_nop 0
	v_pk_mul_f32 v[20:21], v[44:45], v[0:1] op_sel_hi:[1,0]
	v_pk_mul_f32 v[18:19], v[42:43], v[0:1] op_sel_hi:[1,0]
	v_mfma_f32_16x16x32_bf16 v[50:53], v[82:85], v[100:103], v[50:53]
	s_waitcnt lgkmcnt(4)
	v_mfma_f32_16x16x32_bf16 v[42:45], v[74:77], v[22:25], v[18:21]
	s_nop 2
	v_pk_mul_f32 v[20:21], v[40:41], v[0:1] op_sel_hi:[1,0]
	v_pk_mul_f32 v[18:19], v[38:39], v[0:1] op_sel_hi:[1,0]
	s_waitcnt lgkmcnt(2)
	s_nop 0
	v_mfma_f32_16x16x32_bf16 v[38:41], v[70:73], v[22:25], v[18:21]
	s_nop 2
	v_pk_mul_f32 v[20:21], v[36:37], v[0:1] op_sel_hi:[1,0]
	v_pk_mul_f32 v[18:19], v[34:35], v[0:1] op_sel_hi:[1,0]
	s_waitcnt lgkmcnt(0)
	s_setprio 0
	s_nop 0
	v_mfma_f32_16x16x32_bf16 v[34:37], v[66:69], v[22:25], v[18:21]

; #define LAS __attribute__((address_space(3)))
; template <int MODE> ...
;     ...
;         if (t >= act0 && t < act0 + actn) {
;         const LAS unsigned char* Sl = ring + ((t + base) % 3) * SLOT;
; #pragma unroll
;         for (int hf = 0; hf < NH; ++hf) {
;             if (MODE == 1) { const int ks = ktok0 + 64 * t + 32 * hf;
;                 if (ks + 31 < qtok0 - 128 || ks > qtok0 + 31 + 128) continue; }
;             bf16x8 kf[2][2][2];
; #pragma unroll
;             for (int jj = 0; jj < 2; ++jj)
; #pragma unroll
;                 for (int kt = 0; kt < 2; ++kt)
; #pragma unroll
;                     for (int ks = 0; ks < 2; ++ks) kf[jj][kt][ks] = *(const LAS bf16x8*)(Sl + kad[jj][ks] + (32 * hf + 16 * kt) * 128);
;             f32x4 bb[2][2];
; #pragma unroll
;             for (int jj = 0; jj < 2; ++jj) { const LAS f32x4* bl = bcp + ((MODE == 0) ? (dr0 + t - act0) * 8 : 16 * t + 8 * hf) + bofs[jj];
; #pragma unroll
;                 for (int kt = 0; kt < 2; ++kt) bb[jj][kt] = bl[4 * kt]; }
;             s16x4 vlo[2][4], vhi[2][4];
; #pragma unroll
;             for (int jj = 0; jj < 2; ++jj)
; #pragma unroll
;                 for (int dt = 0; dt < 4; ++dt) { const LAS unsigned char* vp = Sl + vad[jj] + (32 * hf) * 128 + ((dt ^ sv) << 5);
;                     vlo[jj][dt] = __builtin_bit_cast(s16x4, __builtin_amdgcn_ds_read_tr16_b64_v4i16((LAS s16x4*)(vp)));
;                     vhi[jj][dt] = __builtin_bit_cast(s16x4, __builtin_amdgcn_ds_read_tr16_b64_v4i16((LAS s16x4*)(vp + 2048))); }
.LBB0_298:
	s_add_i32 s0, s86, 1
	s_mul_hi_i32 s14, s0, 0x55555556
	s_lshr_b32 s15, s14, 31
	s_add_i32 s14, s14, s15
	s_mul_i32 s14, s14, 3
	s_sub_i32 s0, s0, s14
	s_lshl_b32 s0, s0, 14
	s_add_i32 s0, s0, 0
	v_add_u32_e32 v0, s0, v89
	s_lshl_b32 s14, s52, 7
	v_add_u32_e32 v2, s0, v88
	ds_read_b128 v[126:129], v0
	ds_read_b128 v[130:133], v0 offset:2048
	ds_read_b128 v[134:137], v2
	ds_read_b128 v[138:141], v2 offset:2048
	v_add_u32_e32 v0, s0, v92
	s_add_i32 s14, s24, s14
	v_add_u32_e32 v2, s0, v91
	ds_read_b128 v[142:145], v0
	ds_read_b128 v[146:149], v0 offset:2048
	ds_read_b128 v[150:153], v2
	ds_read_b128 v[154:157], v2 offset:2048
	v_lshl_add_u32 v0, v87, 4, s14
	ds_read_b128 v[158:161], v0 offset:128
	ds_read_b128 v[162:165], v0 offset:192
	v_lshl_add_u32 v0, v90, 4, s14
	ds_read_b128 v[166:169], v0 offset:128
	ds_read_b128 v[170:173], v0 offset:192
	v_add3_u32 v0, v86, v122, s0
	v_add_u32_e32 v2, v0, v94
	v_add_u32_e32 v3, v0, v95
	ds_read_b64_tr_b16 v[78:79], v2 offset:8192
	ds_read_b64_tr_b16 v[80:81], v2 offset:10240
	ds_read_b64_tr_b16 v[74:75], v3 offset:8192
	ds_read_b64_tr_b16 v[76:77], v3 offset:10240
	v_add_u32_e32 v2, v0, v96
	v_add_u32_e32 v0, v0, v97
	ds_read_b64_tr_b16 v[70:71], v2 offset:8192
	ds_read_b64_tr_b16 v[72:73], v2 offset:10240
	ds_read_b64_tr_b16 v[66:67], v0 offset:8192
	ds_read_b64_tr_b16 v[68:69], v0 offset:10240
	v_add3_u32 v0, v123, v122, s0
	v_add_u32_e32 v2, v0, v94
	v_add_u32_e32 v3, v0, v95
	ds_read_b64_tr_b16 v[14:15], v2 offset:8192
	ds_read_b64_tr_b16 v[16:17], v2 offset:10240
	ds_read_b64_tr_b16 v[10:11], v3 offset:8192
	ds_read_b64_tr_b16 v[12:13], v3 offset:10240
	v_add_u32_e32 v2, v0, v96
	v_add_u32_e32 v0, v0, v97
	ds_read_b64_tr_b16 v[6:7], v2 offset:8192
	ds_read_b64_tr_b16 v[8:9], v2 offset:10240
	ds_read_b64_tr_b16 v[2:3], v0 offset:8192
	ds_read_b64_tr_b16 v[4:5], v0 offset:10240
	s_waitcnt lgkmcnt(14)
; __device__ __forceinline__ unsigned cvtpk(float lo, float hi) { f32x2 v = {lo, hi}; bf16x2_t b = __builtin_convertvector(v, bf16x2_t); return __builtin_bit_cast(unsigned, b); }
; __device__ __forceinline__ float vmax3(float a, float b, float c) { return __builtin_elementwise_maximum(__builtin_elementwise_maximum(a, b), c); }
; template <int MODE> ...
;     ...
;             f32x4 s[2][2];
; #pragma unroll
;             for (int jj = 0; jj < 2; ++jj)
; #pragma unroll
;                 for (int kt = 0; kt < 2; ++kt) { f32x4 a = (MODE == 0) ? bb[jj][kt] + mneg[jj][kt] : bb[jj][kt];
;                     a = __builtin_amdgcn_mfma_f32_16x16x32_bf16(kf[jj][kt][0], qf[jj][0], a, 0, 0, 0);
;                     s[jj][kt] = __builtin_amdgcn_mfma_f32_16x16x32_bf16(kf[jj][kt][1], qf[jj][1], a, 0, 0, 0); }
;             u32x4 pw[2];
; #pragma unroll
;             for (int jj = 0; jj < 2; ++jj) {
;                 const float tm = vmax3(vmax3(s[jj][0][0], s[jj][0][1], s[jj][0][2]), vmax3(s[jj][0][3], s[jj][1][0], s[jj][1][1]), vmax3(s[jj][1][2], s[jj][1][3], s[jj][1][3]));
;                 const float mn = quad_max3(mrun[jj], tm);
;                 const float alpha = __builtin_amdgcn_exp2f(mrun[jj] - mn);
;                 mrun[jj] = mn;
;                 float rsum = 0.f;
; #pragma unroll
;                 for (int kt = 0; kt < 2; ++kt)
; #pragma unroll
;                     for (int e = 0; e < 4; ++e) { s[jj][kt][e] = __builtin_amdgcn_exp2f(s[jj][kt][e] - mn); rsum += s[jj][kt][e]; }
;                 lrun[jj] = lrun[jj] * alpha + rsum;
; #pragma unroll
;                 for (int dt = 0; dt < 4; ++dt) o[jj][dt] *= alpha;
;                 pw[jj].x = cvtpk(s[jj][0][0], s[jj][0][1]); pw[jj].y = cvtpk(s[jj][0][2], s[jj][0][3]); pw[jj].z = cvtpk(s[jj][1][0], s[jj][1][1]); pw[jj].w = cvtpk(s[jj][1][2], s[jj][1][3]);
;             }
; #pragma unroll
;             for (int jj = 0; jj < 2; ++jj)
; #pragma unroll
;                 for (int dt = 0; dt < 4; ++dt) {
;                     const bf16x8 vf = (bf16x8){vlo[jj][dt][0], vlo[jj][dt][1], vlo[jj][dt][2], vlo[jj][dt][3], vhi[jj][dt][0], vhi[jj][dt][1], vhi[jj][dt][2], vhi[jj][dt][3]};
;                     o[jj][dt] = __builtin_amdgcn_mfma_f32_16x16x32_bf16(vf, __builtin_bit_cast(bf16x8, pw[jj]), o[jj][dt], 0, 0, 0); }
;             __builtin_amdgcn_sched_barrier(0);
	v_pk_add_f32 v[160:161], v[112:113], v[160:161]
	v_pk_add_f32 v[158:159], v[110:111], v[158:159]
	s_nop 1
	v_mfma_f32_16x16x32_bf16 v[126:129], v[126:129], v[30:33], v[158:161]
	s_nop 2
	v_pk_add_f32 v[160:161], v[114:115], v[164:165]
	v_pk_add_f32 v[158:159], v[108:109], v[162:163]
	v_mfma_f32_16x16x32_bf16 v[126:129], v[134:137], v[26:29], v[126:129]
	v_pk_add_f32 v[136:137], v[106:107], v[168:169]
	v_pk_add_f32 v[134:135], v[102:103], v[166:167]
	v_mfma_f32_16x16x32_bf16 v[130:133], v[130:133], v[30:33], v[158:161]
	v_mfma_f32_16x16x32_bf16 v[130:133], v[138:141], v[26:29], v[130:133]
	s_nop 2
	v_maximum3_f32 v0, v126, v127, v128
	v_pk_add_f32 v[160:161], v[104:105], v[172:173]
	v_pk_add_f32 v[158:159], v[100:101], v[170:171]
	v_mfma_f32_16x16x32_bf16 v[134:137], v[142:145], v[22:25], v[134:137]
	v_mfma_f32_16x16x32_bf16 v[134:137], v[150:153], v[18:21], v[134:137]
	v_maximum3_f32 v138, v129, v130, v131
	v_maximum3_f32 v139, v132, v133, v133
	v_maximum3_f32 v0, v0, v138, v139
	v_mov_b32_e32 v138, v0
	s_nop 1
	v_permlane16_swap_b32_e32 v0, v138
	v_maximum3_f32 v0, v0, v138, v138
	v_mov_b32_e32 v138, v0
	s_nop 1
	v_permlane32_swap_b32_e32 v0, v138
	v_maximum3_f32 v162, v125, v0, v138
	v_mfma_f32_16x16x32_bf16 v[138:141], v[146:149], v[22:25], v[158:161]
	v_sub_f32_e32 v0, v125, v162
	v_pk_add_f32 v[200:201], v[126:127], v[162:163] op_sel_hi:[1,0] neg_lo:[0,1] neg_hi:[0,1]
	v_pk_add_f32 v[202:203], v[128:129], v[162:163] op_sel_hi:[1,0] neg_lo:[0,1] neg_hi:[0,1]
	v_pk_add_f32 v[204:205], v[130:131], v[162:163] op_sel_hi:[1,0] neg_lo:[0,1] neg_hi:[0,1]
	v_pk_add_f32 v[206:207], v[132:133], v[162:163] op_sel_hi:[1,0] neg_lo:[0,1] neg_hi:[0,1]
	v_exp_f32_e32 v142, v200
	v_exp_f32_e32 v144, v201
	v_mfma_f32_16x16x32_bf16 v[138:141], v[154:157], v[18:21], v[138:141]
	v_exp_f32_e32 v146, v202
	v_exp_f32_e32 v148, v203
	v_exp_f32_e32 v130, v204
	v_exp_f32_e32 v150, v205
	v_exp_f32_e32 v132, v0
	v_exp_f32_e32 v152, v206
	v_exp_f32_e32 v154, v207
	v_maximum3_f32 v0, v134, v135, v136
	v_maximum3_f32 v125, v137, v138, v139
	v_maximum3_f32 v129, v140, v141, v141
	v_maximum3_f32 v0, v0, v125, v129
	v_mov_b32_e32 v125, v0
	s_nop 1
	v_permlane16_swap_b32_e32 v0, v125
	v_maximum3_f32 v0, v0, v125, v125
	v_mov_b32_e32 v125, v0
	s_nop 1
	v_permlane32_swap_b32_e32 v0, v125
	v_maximum3_f32 v156, v124, v0, v125
	v_pk_mul_f32 v[56:57], v[56:57], v[132:133] op_sel_hi:[1,0]
	v_pk_mul_f32 v[54:55], v[54:55], v[132:133] op_sel_hi:[1,0]
	v_pk_mul_f32 v[64:65], v[64:65], v[132:133] op_sel_hi:[1,0]
	v_pk_mul_f32 v[62:63], v[62:63], v[132:133] op_sel_hi:[1,0]
	v_pk_mul_f32 v[60:61], v[60:61], v[132:133] op_sel_hi:[1,0]
	v_pk_mul_f32 v[58:59], v[58:59], v[132:133] op_sel_hi:[1,0]
	v_pk_mul_f32 v[52:53], v[52:53], v[132:133] op_sel_hi:[1,0]
	v_pk_mul_f32 v[50:51], v[50:51], v[132:133] op_sel_hi:[1,0]
	v_pk_add_f32 v[208:209], v[134:135], v[156:157] op_sel_hi:[1,0] neg_lo:[0,1] neg_hi:[0,1]
	v_pk_add_f32 v[210:211], v[136:137], v[156:157] op_sel_hi:[1,0] neg_lo:[0,1] neg_hi:[0,1]
	v_pk_add_f32 v[212:213], v[138:139], v[156:157] op_sel_hi:[1,0] neg_lo:[0,1] neg_hi:[0,1]
	v_pk_add_f32 v[214:215], v[140:141], v[156:157] op_sel_hi:[1,0] neg_lo:[0,1] neg_hi:[0,1]
	v_exp_f32_e32 v143, v208
	v_exp_f32_e32 v151, v213
	v_exp_f32_e32 v145, v209
	v_sub_f32_e32 v0, v124, v156
	v_exp_f32_e32 v147, v210
	v_exp_f32_e32 v153, v214
	v_exp_f32_e32 v149, v211
	v_exp_f32_e32 v155, v215
	v_exp_f32_e32 v133, v0
	v_exp_f32_e32 v131, v212
	s_setprio 1
	v_cvt_pk_bf16_f32 v126, v142, v144
	v_cvt_pk_bf16_f32 v127, v146, v148
	v_cvt_pk_bf16_f32 v128, v130, v150
	v_cvt_pk_bf16_f32 v129, v152, v154
	v_pk_add_f32 v[124:125], v[142:143], 0 op_sel_hi:[1,0]
	v_mov_b32_e32 v0, v133
	v_pk_add_f32 v[124:125], v[144:145], v[124:125]
	s_waitcnt lgkmcnt(10)
	v_mfma_f32_16x16x32_bf16 v[58:61], v[70:73], v[126:129], v[58:61]
	v_pk_mul_f32 v[48:49], v[48:49], v[0:1] op_sel_hi:[1,0]
	v_pk_mul_f32 v[46:47], v[46:47], v[0:1] op_sel_hi:[1,0]
	v_cvt_pk_bf16_f32 v70, v143, v145
	v_cvt_pk_bf16_f32 v71, v147, v149
	v_cvt_pk_bf16_f32 v72, v131, v151
	v_cvt_pk_bf16_f32 v73, v153, v155
	v_mfma_f32_16x16x32_bf16 v[54:57], v[78:81], v[126:129], v[54:57]
	v_pk_add_f32 v[78:79], v[146:147], v[124:125]
	v_pk_add_f32 v[78:79], v[148:149], v[78:79]
	s_waitcnt lgkmcnt(6)
	v_mfma_f32_16x16x32_bf16 v[46:49], v[14:17], v[70:73], v[46:49]
	v_pk_mul_f32 v[16:17], v[44:45], v[0:1] op_sel_hi:[1,0]
	v_pk_mul_f32 v[14:15], v[42:43], v[0:1] op_sel_hi:[1,0]
	v_mfma_f32_16x16x32_bf16 v[62:65], v[74:77], v[126:129], v[62:65]
	v_pk_add_f32 v[74:75], v[130:131], v[78:79]
	v_pk_add_f32 v[74:75], v[150:151], v[74:75]
	s_waitcnt lgkmcnt(4)
	v_mfma_f32_16x16x32_bf16 v[42:45], v[10:13], v[70:73], v[14:17]
	v_pk_mul_f32 v[12:13], v[40:41], v[0:1] op_sel_hi:[1,0]
	v_pk_mul_f32 v[10:11], v[38:39], v[0:1] op_sel_hi:[1,0]
	v_mfma_f32_16x16x32_bf16 v[50:53], v[66:69], v[126:129], v[50:53]
	v_pk_add_f32 v[66:67], v[152:153], v[74:75]
	v_pk_add_f32 v[14:15], v[154:155], v[66:67]
	s_waitcnt lgkmcnt(2)
	v_mfma_f32_16x16x32_bf16 v[38:41], v[6:9], v[70:73], v[10:13]
	v_pk_mul_f32 v[8:9], v[36:37], v[0:1] op_sel_hi:[1,0]
	v_pk_mul_f32 v[6:7], v[34:35], v[0:1] op_sel_hi:[1,0]
	v_pk_fma_f32 v[98:99], v[98:99], v[132:133], v[14:15]
	s_waitcnt lgkmcnt(0)
	v_mfma_f32_16x16x32_bf16 v[34:37], v[2:5], v[70:73], v[6:9]
	s_setprio 0
	v_mov_b32_e32 v125, v162
	v_mov_b32_e32 v124, v156
	s_cmp_eq_u32 s41, 2
	s_cbranch_scc1 .LBB0_281

; #define LAS __attribute__((address_space(3)))
; template <int MODE> ...
;     ...
;         if (t >= act0 && t < act0 + actn) {
;         const LAS unsigned char* Sl = ring + ((t + base) % 3) * SLOT;
; #pragma unroll
;         for (int hf = 0; hf < NH; ++hf) {
;             if (MODE == 1) { const int ks = ktok0 + 64 * t + 32 * hf;
;                 if (ks + 31 < qtok0 - 128 || ks > qtok0 + 31 + 128) continue; }
;             bf16x8 kf[2][2][2];
; #pragma unroll
;             for (int jj = 0; jj < 2; ++jj)
; #pragma unroll
;                 for (int kt = 0; kt < 2; ++kt)
; #pragma unroll
;                     for (int ks = 0; ks < 2; ++ks) kf[jj][kt][ks] = *(const LAS bf16x8*)(Sl + kad[jj][ks] + (32 * hf + 16 * kt) * 128);
;             f32x4 bb[2][2];
; #pragma unroll
;             for (int jj = 0; jj < 2; ++jj) { const LAS f32x4* bl = bcp + ((MODE == 0) ? (dr0 + t - act0) * 8 : 16 * t + 8 * hf) + bofs[jj];
; #pragma unroll
;                 for (int kt = 0; kt < 2; ++kt) bb[jj][kt] = bl[4 * kt]; }
;             s16x4 vlo[2][4], vhi[2][4];
; #pragma unroll
;             for (int jj = 0; jj < 2; ++jj)
; #pragma unroll
;                 for (int dt = 0; dt < 4; ++dt) { const LAS unsigned char* vp = Sl + vad[jj] + (32 * hf) * 128 + ((dt ^ sv) << 5);
;                     vlo[jj][dt] = __builtin_bit_cast(s16x4, __builtin_amdgcn_ds_read_tr16_b64_v4i16((LAS s16x4*)(vp)));
;                     vhi[jj][dt] = __builtin_bit_cast(s16x4, __builtin_amdgcn_ds_read_tr16_b64_v4i16((LAS s16x4*)(vp + 2048))); }
.LBB0_305:
	s_add_i32 s0, s65, 2
	s_cmp_ge_i32 s0, s23
	s_cselect_b64 s[60:61], -1, 0
	s_cmp_lt_i32 s0, s45
	s_cselect_b64 s[66:67], -1, 0
	s_and_b64 s[60:61], s[60:61], s[66:67]
	s_andn2_b64 vcc, exec, s[60:61]
	s_cbranch_vccnz .LBB0_300
	s_add_i32 s0, s86, s65
	s_add_i32 s0, s0, 2
	s_mul_hi_i32 s14, s0, 0x55555556
	s_lshr_b32 s15, s14, 31
	s_add_i32 s14, s14, s15
	s_mul_i32 s14, s14, 3
	s_sub_i32 s0, s0, s14
	s_lshl_b32 s0, s0, 14
	s_add_i32 s0, s0, 0
	v_add_u32_e32 v2, s0, v89
	v_add_u32_e32 v3, s0, v88
	ds_read_b128 v[130:133], v2
	ds_read_b128 v[134:137], v2 offset:2048
	ds_read_b128 v[138:141], v3
	ds_read_b128 v[142:145], v3 offset:2048
	v_add_u32_e32 v2, s0, v92
	v_add_u32_e32 v3, s0, v91
	ds_read_b128 v[146:149], v2
	ds_read_b128 v[150:153], v2 offset:2048
	ds_read_b128 v[154:157], v3
	ds_read_b128 v[158:161], v3 offset:2048
	v_add_u32_e32 v2, s50, v128
	v_add_u32_e32 v3, s50, v127
	ds_read_b128 v[162:165], v2
	ds_read_b128 v[166:169], v2 offset:64
	ds_read_b128 v[170:173], v3
	ds_read_b128 v[174:177], v3 offset:64
	v_add_u32_e32 v3, s0, v178
	v_add_u32_e32 v4, s0, v179
	ds_read_b64_tr_b16 v[78:79], v3 offset:8192
	ds_read_b64_tr_b16 v[80:81], v3 offset:10240
	ds_read_b64_tr_b16 v[74:75], v4 offset:8192
	ds_read_b64_tr_b16 v[76:77], v4 offset:10240
	v_add_u32_e32 v3, s0, v180
	v_add_u32_e32 v2, s0, v181
	ds_read_b64_tr_b16 v[70:71], v3 offset:8192
	ds_read_b64_tr_b16 v[72:73], v3 offset:10240
	ds_read_b64_tr_b16 v[66:67], v2 offset:8192
	ds_read_b64_tr_b16 v[68:69], v2 offset:10240
	v_add_u32_e32 v3, s0, v182
	v_add_u32_e32 v4, s0, v183
	ds_read_b64_tr_b16 v[14:15], v3 offset:8192
	ds_read_b64_tr_b16 v[16:17], v3 offset:10240
	ds_read_b64_tr_b16 v[10:11], v4 offset:8192
	ds_read_b64_tr_b16 v[12:13], v4 offset:10240
	v_add_u32_e32 v3, s0, v184
	v_add_u32_e32 v4, s0, v185
	ds_read_b64_tr_b16 v[6:7], v3 offset:8192
	ds_read_b64_tr_b16 v[8:9], v3 offset:10240
	ds_read_b64_tr_b16 v[2:3], v4 offset:8192
	ds_read_b64_tr_b16 v[4:5], v4 offset:10240
	s_waitcnt lgkmcnt(14)
; __device__ __forceinline__ unsigned cvtpk(float lo, float hi) { f32x2 v = {lo, hi}; bf16x2_t b = __builtin_convertvector(v, bf16x2_t); return __builtin_bit_cast(unsigned, b); }
; __device__ __forceinline__ float vmax3(float a, float b, float c) { return __builtin_elementwise_maximum(__builtin_elementwise_maximum(a, b), c); }
; template <int MODE> ...
;     ...
;             f32x4 s[2][2];
; #pragma unroll
;             for (int jj = 0; jj < 2; ++jj)
; #pragma unroll
;                 for (int kt = 0; kt < 2; ++kt) { f32x4 a = (MODE == 0) ? bb[jj][kt] + mneg[jj][kt] : bb[jj][kt];
;                     a = __builtin_amdgcn_mfma_f32_16x16x32_bf16(kf[jj][kt][0], qf[jj][0], a, 0, 0, 0);
;                     s[jj][kt] = __builtin_amdgcn_mfma_f32_16x16x32_bf16(kf[jj][kt][1], qf[jj][1], a, 0, 0, 0); }
;             u32x4 pw[2];
; #pragma unroll
;             for (int jj = 0; jj < 2; ++jj) {
;                 const float tm = vmax3(vmax3(s[jj][0][0], s[jj][0][1], s[jj][0][2]), vmax3(s[jj][0][3], s[jj][1][0], s[jj][1][1]), vmax3(s[jj][1][2], s[jj][1][3], s[jj][1][3]));
;                 const float mn = quad_max3(mrun[jj], tm);
;                 const float alpha = __builtin_amdgcn_exp2f(mrun[jj] - mn);
;                 mrun[jj] = mn;
;                 float rsum = 0.f;
; #pragma unroll
;                 for (int kt = 0; kt < 2; ++kt)
; #pragma unroll
;                     for (int e = 0; e < 4; ++e) { s[jj][kt][e] = __builtin_amdgcn_exp2f(s[jj][kt][e] - mn); rsum += s[jj][kt][e]; }
;                 lrun[jj] = lrun[jj] * alpha + rsum;
; #pragma unroll
;                 for (int dt = 0; dt < 4; ++dt) o[jj][dt] *= alpha;
;                 pw[jj].x = cvtpk(s[jj][0][0], s[jj][0][1]); pw[jj].y = cvtpk(s[jj][0][2], s[jj][0][3]); pw[jj].z = cvtpk(s[jj][1][0], s[jj][1][1]); pw[jj].w = cvtpk(s[jj][1][2], s[jj][1][3]);
;             }
; #pragma unroll
;             for (int jj = 0; jj < 2; ++jj)
; #pragma unroll
;                 for (int dt = 0; dt < 4; ++dt) {
;                     const bf16x8 vf = (bf16x8){vlo[jj][dt][0], vlo[jj][dt][1], vlo[jj][dt][2], vlo[jj][dt][3], vhi[jj][dt][0], vhi[jj][dt][1], vhi[jj][dt][2], vhi[jj][dt][3]};
;                     o[jj][dt] = __builtin_amdgcn_mfma_f32_16x16x32_bf16(vf, __builtin_bit_cast(bf16x8, pw[jj]), o[jj][dt], 0, 0, 0); }
;             __builtin_amdgcn_sched_barrier(0);
	v_pk_add_f32 v[164:165], v[112:113], v[164:165]
	v_pk_add_f32 v[162:163], v[110:111], v[162:163]
	s_nop 1
	v_mfma_f32_16x16x32_bf16 v[130:133], v[130:133], v[30:33], v[162:165]
	s_nop 2
	v_pk_add_f32 v[164:165], v[114:115], v[168:169]
	v_pk_add_f32 v[162:163], v[108:109], v[166:167]
	v_mfma_f32_16x16x32_bf16 v[130:133], v[138:141], v[26:29], v[130:133]
	v_pk_add_f32 v[140:141], v[106:107], v[172:173]
	v_pk_add_f32 v[138:139], v[102:103], v[170:171]
	v_mfma_f32_16x16x32_bf16 v[134:137], v[134:137], v[30:33], v[162:165]
	v_mfma_f32_16x16x32_bf16 v[134:137], v[142:145], v[26:29], v[134:137]
	s_nop 2
	v_maximum3_f32 v129, v130, v131, v132
	v_pk_add_f32 v[164:165], v[104:105], v[176:177]
	v_pk_add_f32 v[162:163], v[100:101], v[174:175]
	v_mfma_f32_16x16x32_bf16 v[138:141], v[146:149], v[22:25], v[138:141]
	v_mfma_f32_16x16x32_bf16 v[138:141], v[154:157], v[18:21], v[138:141]
	v_maximum3_f32 v142, v133, v134, v135
	v_maximum3_f32 v143, v136, v137, v137
	v_maximum3_f32 v129, v129, v142, v143
	v_mov_b32_e32 v142, v129
	s_nop 1
	v_permlane16_swap_b32_e32 v129, v142
	v_maximum3_f32 v129, v129, v142, v142
	v_mov_b32_e32 v142, v129
	s_nop 1
	v_permlane32_swap_b32_e32 v129, v142
	v_maximum3_f32 v129, v125, v129, v142
	v_mfma_f32_16x16x32_bf16 v[142:145], v[150:153], v[22:25], v[162:165]
	v_pk_add_f32 v[130:131], v[130:131], v[128:129] op_sel:[0,1] op_sel_hi:[1,1] neg_lo:[0,1] neg_hi:[0,1]
	v_pk_add_f32 v[132:133], v[132:133], v[128:129] op_sel:[0,1] op_sel_hi:[1,1] neg_lo:[0,1] neg_hi:[0,1]
	v_pk_add_f32 v[134:135], v[134:135], v[128:129] op_sel:[0,1] op_sel_hi:[1,1] neg_lo:[0,1] neg_hi:[0,1]
	v_pk_add_f32 v[136:137], v[136:137], v[128:129] op_sel:[0,1] op_sel_hi:[1,1] neg_lo:[0,1] neg_hi:[0,1]
	v_sub_f32_e32 v125, v125, v129
	v_mfma_f32_16x16x32_bf16 v[142:145], v[158:161], v[18:21], v[142:145]
	v_exp_f32_e32 v146, v130
	v_exp_f32_e32 v148, v131
	v_exp_f32_e32 v150, v132
	v_exp_f32_e32 v152, v133
	v_exp_f32_e32 v154, v135
	v_exp_f32_e32 v156, v136
	v_exp_f32_e32 v158, v137
	v_exp_f32_e32 v134, v134
	v_exp_f32_e32 v136, v125
	v_maximum3_f32 v125, v138, v139, v140
	v_maximum3_f32 v133, v141, v142, v143
	v_maximum3_f32 v135, v144, v145, v145
	v_maximum3_f32 v125, v125, v133, v135
	v_mov_b32_e32 v133, v125
	s_nop 1
	v_permlane16_swap_b32_e32 v125, v133
	v_maximum3_f32 v125, v125, v133, v133
	v_mov_b32_e32 v133, v125
	s_nop 1
	v_permlane32_swap_b32_e32 v125, v133
	v_maximum3_f32 v160, v124, v125, v133
	v_pk_add_f32 v[138:139], v[138:139], v[160:161] op_sel_hi:[1,0] neg_lo:[0,1] neg_hi:[0,1]
	v_pk_add_f32 v[140:141], v[140:141], v[160:161] op_sel_hi:[1,0] neg_lo:[0,1] neg_hi:[0,1]
	v_pk_add_f32 v[142:143], v[142:143], v[160:161] op_sel_hi:[1,0] neg_lo:[0,1] neg_hi:[0,1]
	v_pk_add_f32 v[144:145], v[144:145], v[160:161] op_sel_hi:[1,0] neg_lo:[0,1] neg_hi:[0,1]
	v_sub_f32_e32 v137, v124, v160
	v_exp_f32_e32 v147, v138
	v_pk_mul_f32 v[56:57], v[56:57], v[136:137] op_sel_hi:[1,0]
	v_exp_f32_e32 v149, v139
	v_pk_mul_f32 v[54:55], v[54:55], v[136:137] op_sel_hi:[1,0]
	v_exp_f32_e32 v151, v140
	v_pk_mul_f32 v[64:65], v[64:65], v[136:137] op_sel_hi:[1,0]
	v_exp_f32_e32 v153, v141
	v_pk_mul_f32 v[62:63], v[62:63], v[136:137] op_sel_hi:[1,0]
	v_exp_f32_e32 v155, v143
	v_pk_mul_f32 v[60:61], v[60:61], v[136:137] op_sel_hi:[1,0]
	v_exp_f32_e32 v157, v144
	v_pk_mul_f32 v[58:59], v[58:59], v[136:137] op_sel_hi:[1,0]
	v_exp_f32_e32 v159, v145
	v_pk_mul_f32 v[52:53], v[52:53], v[136:137] op_sel_hi:[1,0]
	v_exp_f32_e32 v135, v142
	v_pk_mul_f32 v[50:51], v[50:51], v[136:137] op_sel_hi:[1,0]
	v_exp_f32_e32 v137, v137
	s_setprio 1
	v_cvt_pk_bf16_f32 v130, v146, v148
	v_cvt_pk_bf16_f32 v131, v150, v152
	v_cvt_pk_bf16_f32 v132, v134, v154
	v_cvt_pk_bf16_f32 v133, v156, v158
	s_waitcnt lgkmcnt(12)
	v_mfma_f32_16x16x32_bf16 v[62:65], v[74:77], v[130:133], v[62:65]
	v_pk_add_f32 v[124:125], v[146:147], v[148:149]
	v_pk_mul_f32 v[48:49], v[48:49], v[136:137] op_sel:[0,1] op_sel_hi:[1,1]
	s_waitcnt lgkmcnt(10)
	v_mfma_f32_16x16x32_bf16 v[58:61], v[70:73], v[130:133], v[58:61]
	v_pk_mul_f32 v[46:47], v[46:47], v[136:137] op_sel:[0,1] op_sel_hi:[1,1]
	v_cvt_pk_bf16_f32 v70, v147, v149
	v_cvt_pk_bf16_f32 v71, v151, v153
	v_cvt_pk_bf16_f32 v72, v135, v155
	v_cvt_pk_bf16_f32 v73, v157, v159
	v_mfma_f32_16x16x32_bf16 v[54:57], v[78:81], v[130:133], v[54:57]
	v_pk_add_f32 v[78:79], v[150:151], v[124:125]
	v_pk_add_f32 v[78:79], v[152:153], v[78:79]
	s_waitcnt lgkmcnt(6)
	v_mfma_f32_16x16x32_bf16 v[46:49], v[14:17], v[70:73], v[46:49]
	v_pk_mul_f32 v[16:17], v[44:45], v[136:137] op_sel:[0,1] op_sel_hi:[1,1]
	v_pk_mul_f32 v[14:15], v[42:43], v[136:137] op_sel:[0,1] op_sel_hi:[1,1]
	v_pk_add_f32 v[74:75], v[134:135], v[78:79]
	v_mfma_f32_16x16x32_bf16 v[50:53], v[66:69], v[130:133], v[50:53]
	v_pk_add_f32 v[74:75], v[154:155], v[74:75]
	v_pk_add_f32 v[66:67], v[156:157], v[74:75]
	s_waitcnt lgkmcnt(4)
	v_mfma_f32_16x16x32_bf16 v[42:45], v[10:13], v[70:73], v[14:17]
	v_pk_mul_f32 v[12:13], v[40:41], v[136:137] op_sel:[0,1] op_sel_hi:[1,1]
	v_pk_mul_f32 v[10:11], v[38:39], v[136:137] op_sel:[0,1] op_sel_hi:[1,1]
	v_pk_add_f32 v[14:15], v[158:159], v[66:67]
	s_waitcnt lgkmcnt(2)
	v_mfma_f32_16x16x32_bf16 v[38:41], v[6:9], v[70:73], v[10:13]
	v_pk_mul_f32 v[8:9], v[36:37], v[136:137] op_sel:[0,1] op_sel_hi:[1,1]
	v_pk_mul_f32 v[6:7], v[34:35], v[136:137] op_sel:[0,1] op_sel_hi:[1,1]
	v_pk_fma_f32 v[98:99], v[98:99], v[136:137], v[14:15]
	s_waitcnt lgkmcnt(0)
	v_mfma_f32_16x16x32_bf16 v[34:37], v[2:5], v[70:73], v[6:9]
	s_setprio 0
	v_mov_b32_e32 v125, v129
	v_mov_b32_e32 v124, v160
	s_branch .LBB0_300

; template <int MODE> ...
;     ...
;         if (t >= act0 && t < act0 + actn) {
;         const LAS unsigned char* Sl = ring + ((t + base) % 3) * SLOT;
; #pragma unroll
;         for (int hf = 0; hf < NH; ++hf) {
;             if (MODE == 1) { const int ks = ktok0 + 64 * t + 32 * hf;
;                 if (ks + 31 < qtok0 - 128 || ks > qtok0 + 31 + 128) continue; }
;             bf16x8 kf[2][2][2];
; #pragma unroll
;             for (int jj = 0; jj < 2; ++jj)
; #pragma unroll
;                 for (int kt = 0; kt < 2; ++kt)
; #pragma unroll
;                     for (int ks = 0; ks < 2; ++ks) kf[jj][kt][ks] = *(const LAS bf16x8*)(Sl + kad[jj][ks] + (32 * hf + 16 * kt) * 128);
;             f32x4 bb[2][2];
; #pragma unroll
;             for (int jj = 0; jj < 2; ++jj) { const LAS f32x4* bl = bcp + ((MODE == 0) ? (dr0 + t - act0) * 8 : 16 * t + 8 * hf) + bofs[jj];
; #pragma unroll
;                 for (int kt = 0; kt < 2; ++kt) bb[jj][kt] = bl[4 * kt]; }
;             s16x4 vlo[2][4], vhi[2][4];
; #pragma unroll
;             for (int jj = 0; jj < 2; ++jj)
; #pragma unroll
;                 for (int dt = 0; dt < 4; ++dt) { const LAS unsigned char* vp = Sl + vad[jj] + (32 * hf) * 128 + ((dt ^ sv) << 5);
;                     vlo[jj][dt] = __builtin_bit_cast(s16x4, __builtin_amdgcn_ds_read_tr16_b64_v4i16((LAS s16x4*)(vp)));
;                     vhi[jj][dt] = __builtin_bit_cast(s16x4, __builtin_amdgcn_ds_read_tr16_b64_v4i16((LAS s16x4*)(vp + 2048))); }
;             __builtin_amdgcn_sched_barrier(0);
;             f32x4 s[2][2];
; #pragma unroll
;             for (int jj = 0; jj < 2; ++jj)
; #pragma unroll
;                 for (int kt = 0; kt < 2; ++kt) { f32x4 a = (MODE == 0) ? bb[jj][kt] + mneg[jj][kt] : bb[jj][kt];
;                     a = __builtin_amdgcn_mfma_f32_16x16x32_bf16(kf[jj][kt][0], qf[jj][0], a, 0, 0, 0);
;                     s[jj][kt] = __builtin_amdgcn_mfma_f32_16x16x32_bf16(kf[jj][kt][1], qf[jj][1], a, 0, 0, 0); }
;             u32x4 pw[2];
; #pragma unroll
;             for (int jj = 0; jj < 2; ++jj) {
;                 const float tm = vmax3(vmax3(s[jj][0][0], s[jj][0][1], s[jj][0][2]), vmax3(s[jj][0][3], s[jj][1][0], s[jj][1][1]), vmax3(s[jj][1][2], s[jj][1][3], s[jj][1][3]));
;                 const float mn = quad_max3(mrun[jj], tm);
;                 const float alpha = __builtin_amdgcn_exp2f(mrun[jj] - mn);
;                 mrun[jj] = mn;
.LBB0_343:
	s_add_i32 s0, s86, s65
	s_mul_hi_i32 s14, s0, 0x55555556
	s_lshr_b32 s15, s14, 31
	s_add_i32 s14, s14, s15
	s_mul_i32 s14, s14, 3
	s_sub_i32 s0, s0, s14
	s_lshl_b32 s0, s0, 14
	s_add_i32 s0, s0, 0
	s_add_i32 s14, s27, 31
	s_cmp_lt_i32 s14, s41
	s_cselect_b64 s[50:51], -1, 0
	s_cmp_gt_i32 s27, s45
	s_cselect_b64 s[52:53], -1, 0
	s_or_b64 s[50:51], s[50:51], s[52:53]
	v_add_u32_e32 v0, s0, v78
	s_and_b64 vcc, exec, s[50:51]
	v_add_u32_e32 v98, s0, v70
	v_add_u32_e32 v97, s0, v71
	v_add_u32_e32 v96, s40, v80
	v_add_u32_e32 v85, s40, v79
	v_add_u32_e32 v84, v0, v74
	v_add_u32_e32 v83, v0, v75
	v_add_u32_e32 v81, v0, v76
	v_add_u32_e32 v0, v0, v77
	s_cbranch_vccnz .LBB0_345
	v_add_u32_e32 v2, 0x10000, v96
	v_add_u32_e32 v3, 0x10040, v96
	ds_read_b128 v[100:103], v98
	ds_read_b128 v[104:107], v98 offset:2048
	ds_read_b128 v[108:111], v97
	ds_read_b128 v[112:115], v97 offset:2048
	ds_read_b128 v[118:121], v2
	ds_read_b128 v[122:125], v3
	v_add_u32_e32 v2, 0x10000, v85
	v_add_u32_e32 v3, 0x10040, v85
	ds_read_b128 v[126:129], v2
	ds_read_b128 v[130:133], v3
	ds_read_b64_tr_b16 v[14:15], v84 offset:8192
	ds_read_b64_tr_b16 v[16:17], v84 offset:10240
	ds_read_b64_tr_b16 v[10:11], v83 offset:8192
	ds_read_b64_tr_b16 v[12:13], v83 offset:10240
	ds_read_b64_tr_b16 v[6:7], v81 offset:8192
	ds_read_b64_tr_b16 v[8:9], v81 offset:10240
	ds_read_b64_tr_b16 v[2:3], v0 offset:8192
	ds_read_b64_tr_b16 v[4:5], v0 offset:10240
	s_waitcnt lgkmcnt(11)
	v_mfma_f32_16x16x32_bf16 v[118:121], v[100:103], v[30:33], v[118:121]
	s_waitcnt lgkmcnt(10)
	v_mfma_f32_16x16x32_bf16 v[122:125], v[104:107], v[30:33], v[122:125]
	v_mfma_f32_16x16x32_bf16 v[118:121], v[108:111], v[26:29], v[118:121]
	v_mfma_f32_16x16x32_bf16 v[122:125], v[112:115], v[26:29], v[122:125]
	s_waitcnt lgkmcnt(9)
	v_mfma_f32_16x16x32_bf16 v[100:103], v[100:103], v[22:25], v[126:129]
	s_nop 4
	v_maximum3_f32 v99, v118, v119, v120
	v_mfma_f32_16x16x32_bf16 v[100:103], v[108:111], v[18:21], v[100:103]
	v_maximum3_f32 v108, v121, v122, v123
	v_maximum3_f32 v109, v124, v125, v125
	v_maximum3_f32 v99, v99, v108, v109
	s_waitcnt lgkmcnt(8)
	v_mfma_f32_16x16x32_bf16 v[104:107], v[104:107], v[22:25], v[130:133]
	v_mov_b32_e32 v108, v99
	s_nop 1
	v_permlane16_swap_b32_e32 v99, v108
	v_maximum3_f32 v99, v99, v108, v108
	v_mfma_f32_16x16x32_bf16 v[104:107], v[112:115], v[18:21], v[104:107]
	v_mov_b32_e32 v108, v99
	s_nop 1
	v_permlane32_swap_b32_e32 v99, v108
	v_maximum3_f32 v99, v82, v99, v108
	v_sub_f32_e32 v82, v82, v99
	v_exp_f32_e32 v130, v82
	v_maximum3_f32 v82, v100, v101, v102
	v_maximum3_f32 v113, v103, v104, v105
	v_maximum3_f32 v115, v106, v107, v107
	v_maximum3_f32 v82, v82, v113, v115
	v_mov_b32_e32 v113, v82
	s_nop 1
	v_permlane16_swap_b32_e32 v82, v113
	v_maximum3_f32 v82, v82, v113, v113
	v_mov_b32_e32 v113, v82
	s_nop 1
	v_permlane32_swap_b32_e32 v82, v113
	v_maximum3_f32 v117, v95, v82, v113
	v_pk_add_f32 v[200:201], v[118:119], v[98:99] op_sel:[0,1] op_sel_hi:[1,1] neg_lo:[0,1] neg_hi:[0,1]
	v_pk_add_f32 v[202:203], v[120:121], v[98:99] op_sel:[0,1] op_sel_hi:[1,1] neg_lo:[0,1] neg_hi:[0,1]
	v_pk_add_f32 v[204:205], v[122:123], v[98:99] op_sel:[0,1] op_sel_hi:[1,1] neg_lo:[0,1] neg_hi:[0,1]
	v_pk_add_f32 v[206:207], v[124:125], v[98:99] op_sel:[0,1] op_sel_hi:[1,1] neg_lo:[0,1] neg_hi:[0,1]
	v_sub_f32_e32 v82, v95, v117
	v_pk_add_f32 v[208:209], v[100:101], v[116:117] op_sel:[0,1] op_sel_hi:[1,1] neg_lo:[0,1] neg_hi:[0,1]
	v_pk_add_f32 v[210:211], v[102:103], v[116:117] op_sel:[0,1] op_sel_hi:[1,1] neg_lo:[0,1] neg_hi:[0,1]
	v_pk_add_f32 v[212:213], v[104:105], v[116:117] op_sel:[0,1] op_sel_hi:[1,1] neg_lo:[0,1] neg_hi:[0,1]
	v_pk_add_f32 v[214:215], v[106:107], v[116:117] op_sel:[0,1] op_sel_hi:[1,1] neg_lo:[0,1] neg_hi:[0,1]
	v_exp_f32_e32 v112, v200
	v_exp_f32_e32 v113, v208
	v_exp_f32_e32 v114, v201
	v_exp_f32_e32 v115, v209
	v_exp_f32_e32 v118, v202
	v_exp_f32_e32 v119, v210
	v_exp_f32_e32 v120, v203
	v_exp_f32_e32 v121, v211
	v_exp_f32_e32 v122, v204
	v_exp_f32_e32 v123, v212
	v_pk_add_f32 v[100:101], v[112:113], 0 op_sel_hi:[1,0]
	v_exp_f32_e32 v126, v205
	v_exp_f32_e32 v127, v213
	v_pk_add_f32 v[100:101], v[114:115], v[100:101]
	v_exp_f32_e32 v124, v206
	v_exp_f32_e32 v125, v214
	v_pk_add_f32 v[100:101], v[118:119], v[100:101]
	v_exp_f32_e32 v128, v207
	v_pk_mul_f32 v[52:53], v[52:53], v[130:131] op_sel_hi:[1,0]
	v_pk_mul_f32 v[50:51], v[50:51], v[130:131] op_sel_hi:[1,0]
	v_pk_mul_f32 v[56:57], v[56:57], v[130:131] op_sel_hi:[1,0]
	v_pk_mul_f32 v[54:55], v[54:55], v[130:131] op_sel_hi:[1,0]
	v_pk_mul_f32 v[60:61], v[60:61], v[130:131] op_sel_hi:[1,0]
	v_pk_mul_f32 v[58:59], v[58:59], v[130:131] op_sel_hi:[1,0]
	v_pk_mul_f32 v[64:65], v[64:65], v[130:131] op_sel_hi:[1,0]
	v_pk_mul_f32 v[62:63], v[62:63], v[130:131] op_sel_hi:[1,0]
	v_exp_f32_e32 v129, v215
	v_pk_add_f32 v[100:101], v[120:121], v[100:101]
	v_exp_f32_e32 v131, v82
	v_pk_add_f32 v[100:101], v[122:123], v[100:101]
	v_cvt_pk_bf16_f32 v108, v112, v114
	v_pk_add_f32 v[100:101], v[126:127], v[100:101]
	v_mov_b32_e32 v82, v131
	v_pk_add_f32 v[100:101], v[124:125], v[100:101]
	v_cvt_pk_bf16_f32 v109, v118, v120
	v_pk_add_f32 v[100:101], v[128:129], v[100:101]
	v_cvt_pk_bf16_f32 v110, v122, v126
	v_cvt_pk_bf16_f32 v111, v124, v128
	v_pk_fma_f32 v[88:89], v[88:89], v[130:131], v[100:101]
	s_setprio 1
	v_pk_mul_f32 v[36:37], v[36:37], v[82:83] op_sel_hi:[1,0]
	v_pk_mul_f32 v[34:35], v[34:35], v[82:83] op_sel_hi:[1,0]
	v_pk_mul_f32 v[40:41], v[40:41], v[82:83] op_sel_hi:[1,0]
	v_pk_mul_f32 v[38:39], v[38:39], v[82:83] op_sel_hi:[1,0]
	v_pk_mul_f32 v[44:45], v[44:45], v[82:83] op_sel_hi:[1,0]
	v_pk_mul_f32 v[42:43], v[42:43], v[82:83] op_sel_hi:[1,0]
	v_pk_mul_f32 v[48:49], v[48:49], v[82:83] op_sel_hi:[1,0]
	v_pk_mul_f32 v[46:47], v[46:47], v[82:83] op_sel_hi:[1,0]
	v_cvt_pk_bf16_f32 v100, v113, v115
	v_cvt_pk_bf16_f32 v101, v119, v121
	v_cvt_pk_bf16_f32 v102, v123, v127
	v_cvt_pk_bf16_f32 v103, v125, v129
	s_waitcnt lgkmcnt(6)
	v_mfma_f32_16x16x32_bf16 v[50:53], v[14:17], v[108:111], v[50:53]
	s_waitcnt lgkmcnt(4)
	v_mfma_f32_16x16x32_bf16 v[54:57], v[10:13], v[108:111], v[54:57]
	s_waitcnt lgkmcnt(2)
	v_mfma_f32_16x16x32_bf16 v[58:61], v[6:9], v[108:111], v[58:61]
	s_waitcnt lgkmcnt(0)
	v_mfma_f32_16x16x32_bf16 v[62:65], v[2:5], v[108:111], v[62:65]
	v_mfma_f32_16x16x32_bf16 v[34:37], v[14:17], v[100:103], v[34:37]
	v_mfma_f32_16x16x32_bf16 v[38:41], v[10:13], v[100:103], v[38:41]
	v_mfma_f32_16x16x32_bf16 v[42:45], v[6:9], v[100:103], v[42:45]
	v_mfma_f32_16x16x32_bf16 v[46:49], v[2:5], v[100:103], v[46:49]
	s_setprio 0
	v_mov_b32_e32 v82, v99
	v_mov_b32_e32 v95, v117
; #define LAS __attribute__((address_space(3)))
; template <int MODE> ...
;     ...
;             if (MODE == 1) { const int ks = ktok0 + 64 * t + 32 * hf;
;                 if (ks + 31 < qtok0 - 128 || ks > qtok0 + 31 + 128) continue; }
;             bf16x8 kf[2][2][2];
; #pragma unroll
;             for (int jj = 0; jj < 2; ++jj)
; #pragma unroll
;                 for (int kt = 0; kt < 2; ++kt)
; #pragma unroll
;                     for (int ks = 0; ks < 2; ++ks) kf[jj][kt][ks] = *(const LAS bf16x8*)(Sl + kad[jj][ks] + (32 * hf + 16 * kt) * 128);
;             f32x4 bb[2][2];
; #pragma unroll
;             for (int jj = 0; jj < 2; ++jj) { const LAS f32x4* bl = bcp + ((MODE == 0) ? (dr0 + t - act0) * 8 : 16 * t + 8 * hf) + bofs[jj];
; #pragma unroll
;                 for (int kt = 0; kt < 2; ++kt) bb[jj][kt] = bl[4 * kt]; }
;             s16x4 vlo[2][4], vhi[2][4];
; #pragma unroll
;             for (int jj = 0; jj < 2; ++jj)
; #pragma unroll
;                 for (int dt = 0; dt < 4; ++dt) { const LAS unsigned char* vp = Sl + vad[jj] + (32 * hf) * 128 + ((dt ^ sv) << 5);
;                     vlo[jj][dt] = __builtin_bit_cast(s16x4, __builtin_amdgcn_ds_read_tr16_b64_v4i16((LAS s16x4*)(vp)));
;                     vhi[jj][dt] = __builtin_bit_cast(s16x4, __builtin_amdgcn_ds_read_tr16_b64_v4i16((LAS s16x4*)(vp + 2048))); }
;             __builtin_amdgcn_sched_barrier(0);
;             f32x4 s[2][2];
; #pragma unroll
;             for (int jj = 0; jj < 2; ++jj)
; #pragma unroll
;                 for (int kt = 0; kt < 2; ++kt) { f32x4 a = (MODE == 0) ? bb[jj][kt] + mneg[jj][kt] : bb[jj][kt];
;                     a = __builtin_amdgcn_mfma_f32_16x16x32_bf16(kf[jj][kt][0], qf[jj][0], a, 0, 0, 0);
;                     s[jj][kt] = __builtin_amdgcn_mfma_f32_16x16x32_bf16(kf[jj][kt][1], qf[jj][1], a, 0, 0, 0); }
;             u32x4 pw[2];
; #pragma unroll
;             for (int jj = 0; jj < 2; ++jj) {
;                 const float tm = vmax3(vmax3(s[jj][0][0], s[jj][0][1], s[jj][0][2]), vmax3(s[jj][0][3], s[jj][1][0], s[jj][1][1]), vmax3(s[jj][1][2], s[jj][1][3], s[jj][1][3]));
;                 const float mn = quad_max3(mrun[jj], tm);
;                 const float alpha = __builtin_amdgcn_exp2f(mrun[jj] - mn);
;                 mrun[jj] = mn;
;                 float rsum = 0.f;
; #pragma unroll
;                 for (int kt = 0; kt < 2; ++kt)
; #pragma unroll
.LBB0_345:
	s_add_i32 s0, s27, 32
	s_add_i32 s14, s27, 63
	s_cmp_lt_i32 s14, s41
	s_cselect_b64 s[50:51], -1, 0
	s_cmp_gt_i32 s0, s45
	s_cselect_b64 s[52:53], -1, 0
	s_or_b64 s[50:51], s[50:51], s[52:53]
	s_and_b64 vcc, exec, s[50:51]
	s_cbranch_vccnz .LBB0_333
	v_add_u32_e32 v2, 0x10080, v96
	v_add_u32_e32 v3, 0x100c0, v96
	ds_read_b128 v[100:103], v98 offset:4096
	ds_read_b128 v[104:107], v98 offset:6144
	ds_read_b128 v[108:111], v97 offset:4096
	ds_read_b128 v[112:115], v97 offset:6144
	ds_read_b128 v[96:99], v2
	ds_read_b128 v[118:121], v3
	v_add_u32_e32 v2, 0x10080, v85
	v_add_u32_e32 v3, 0x100c0, v85
	ds_read_b128 v[122:125], v2
	ds_read_b128 v[126:129], v3
	ds_read_b64_tr_b16 v[14:15], v84 offset:12288
	ds_read_b64_tr_b16 v[16:17], v84 offset:14336
	ds_read_b64_tr_b16 v[10:11], v83 offset:12288
	ds_read_b64_tr_b16 v[12:13], v83 offset:14336
	ds_read_b64_tr_b16 v[6:7], v81 offset:12288
	ds_read_b64_tr_b16 v[8:9], v81 offset:14336
	ds_read_b64_tr_b16 v[2:3], v0 offset:12288
	ds_read_b64_tr_b16 v[4:5], v0 offset:14336
	s_waitcnt lgkmcnt(11)
	v_mfma_f32_16x16x32_bf16 v[96:99], v[100:103], v[30:33], v[96:99]
	s_waitcnt lgkmcnt(10)
	v_mfma_f32_16x16x32_bf16 v[118:121], v[104:107], v[30:33], v[118:121]
	v_mfma_f32_16x16x32_bf16 v[96:99], v[108:111], v[26:29], v[96:99]
	v_mfma_f32_16x16x32_bf16 v[118:121], v[112:115], v[26:29], v[118:121]
	s_waitcnt lgkmcnt(9)
	v_mfma_f32_16x16x32_bf16 v[100:103], v[100:103], v[22:25], v[122:125]
	s_nop 4
	v_maximum3_f32 v0, v96, v97, v98
	v_maximum3_f32 v81, v99, v118, v119
	v_maximum3_f32 v83, v120, v121, v121
	v_maximum3_f32 v0, v0, v81, v83
	v_mov_b32_e32 v81, v0
	s_waitcnt lgkmcnt(8)
	v_mfma_f32_16x16x32_bf16 v[104:107], v[104:107], v[22:25], v[126:129]
	v_permlane16_swap_b32_e32 v0, v81
	v_maximum3_f32 v0, v0, v81, v81
	v_mov_b32_e32 v81, v0
	s_nop 1
	v_permlane32_swap_b32_e32 v0, v81
	v_mfma_f32_16x16x32_bf16 v[100:103], v[108:111], v[18:21], v[100:103]
	v_maximum3_f32 v81, v82, v0, v81
	v_sub_f32_e32 v0, v82, v81
	v_pk_add_f32 v[200:201], v[96:97], v[80:81] op_sel:[0,1] op_sel_hi:[1,1] neg_lo:[0,1] neg_hi:[0,1]
	v_pk_add_f32 v[202:203], v[98:99], v[80:81] op_sel:[0,1] op_sel_hi:[1,1] neg_lo:[0,1] neg_hi:[0,1]
	v_pk_add_f32 v[204:205], v[118:119], v[80:81] op_sel:[0,1] op_sel_hi:[1,1] neg_lo:[0,1] neg_hi:[0,1]
	v_pk_add_f32 v[206:207], v[120:121], v[80:81] op_sel:[0,1] op_sel_hi:[1,1] neg_lo:[0,1] neg_hi:[0,1]
	v_mfma_f32_16x16x32_bf16 v[104:107], v[112:115], v[18:21], v[104:107]
	v_exp_f32_e32 v96, v200
	v_exp_f32_e32 v108, v201
	v_exp_f32_e32 v98, v202
	v_exp_f32_e32 v122, v0
	v_maximum3_f32 v0, v100, v101, v102
	v_maximum3_f32 v97, v103, v104, v105
	v_maximum3_f32 v99, v106, v107, v107
	v_maximum3_f32 v0, v0, v97, v99
	v_mov_b32_e32 v97, v0
	s_nop 1
	v_permlane16_swap_b32_e32 v0, v97
	v_maximum3_f32 v0, v0, v97, v97
	v_mov_b32_e32 v97, v0
	s_nop 1
	v_permlane32_swap_b32_e32 v0, v97
	v_maximum3_f32 v117, v95, v0, v97
	v_sub_f32_e32 v0, v95, v117
	v_pk_add_f32 v[208:209], v[100:101], v[116:117] op_sel:[0,1] op_sel_hi:[1,1] neg_lo:[0,1] neg_hi:[0,1]
	v_pk_add_f32 v[210:211], v[102:103], v[116:117] op_sel:[0,1] op_sel_hi:[1,1] neg_lo:[0,1] neg_hi:[0,1]
	v_pk_add_f32 v[212:213], v[104:105], v[116:117] op_sel:[0,1] op_sel_hi:[1,1] neg_lo:[0,1] neg_hi:[0,1]
	v_pk_add_f32 v[214:215], v[106:107], v[116:117] op_sel:[0,1] op_sel_hi:[1,1] neg_lo:[0,1] neg_hi:[0,1]
	v_exp_f32_e32 v97, v208
	v_exp_f32_e32 v109, v209
	v_exp_f32_e32 v99, v210
	v_exp_f32_e32 v110, v203
	v_exp_f32_e32 v111, v211
	v_exp_f32_e32 v112, v204
	v_exp_f32_e32 v113, v212
	v_exp_f32_e32 v114, v205
	v_exp_f32_e32 v115, v213
	v_exp_f32_e32 v118, v206
	v_pk_mul_f32 v[52:53], v[52:53], v[122:123] op_sel_hi:[1,0]
	v_pk_mul_f32 v[50:51], v[50:51], v[122:123] op_sel_hi:[1,0]
	v_pk_mul_f32 v[56:57], v[56:57], v[122:123] op_sel_hi:[1,0]
	v_pk_mul_f32 v[54:55], v[54:55], v[122:123] op_sel_hi:[1,0]
	v_pk_mul_f32 v[60:61], v[60:61], v[122:123] op_sel_hi:[1,0]
	v_pk_mul_f32 v[58:59], v[58:59], v[122:123] op_sel_hi:[1,0]
	v_pk_mul_f32 v[64:65], v[64:65], v[122:123] op_sel_hi:[1,0]
	v_pk_mul_f32 v[62:63], v[62:63], v[122:123] op_sel_hi:[1,0]
	v_exp_f32_e32 v119, v214
	v_exp_f32_e32 v123, v0
	v_exp_f32_e32 v120, v207
	v_pk_add_f32 v[100:101], v[96:97], 0 op_sel_hi:[1,0]
	v_exp_f32_e32 v121, v215
	v_pk_add_f32 v[100:101], v[108:109], v[100:101]
	v_mov_b32_e32 v0, v123
	v_pk_add_f32 v[100:101], v[98:99], v[100:101]
	v_cvt_pk_bf16_f32 v82, v96, v108
	v_pk_add_f32 v[100:101], v[110:111], v[100:101]
	v_cvt_pk_bf16_f32 v83, v98, v110
	s_setprio 1
	v_cvt_pk_bf16_f32 v84, v112, v114
	v_cvt_pk_bf16_f32 v85, v118, v120
	v_pk_add_f32 v[100:101], v[112:113], v[100:101]
	v_pk_mul_f32 v[36:37], v[36:37], v[0:1] op_sel_hi:[1,0]
	v_pk_mul_f32 v[34:35], v[34:35], v[0:1] op_sel_hi:[1,0]
	v_pk_mul_f32 v[40:41], v[40:41], v[0:1] op_sel_hi:[1,0]
	v_pk_mul_f32 v[38:39], v[38:39], v[0:1] op_sel_hi:[1,0]
	v_pk_mul_f32 v[44:45], v[44:45], v[0:1] op_sel_hi:[1,0]
	v_pk_mul_f32 v[42:43], v[42:43], v[0:1] op_sel_hi:[1,0]
	v_pk_mul_f32 v[48:49], v[48:49], v[0:1] op_sel_hi:[1,0]
	v_pk_mul_f32 v[46:47], v[46:47], v[0:1] op_sel_hi:[1,0]
	v_cvt_pk_bf16_f32 v96, v97, v109
	v_cvt_pk_bf16_f32 v97, v99, v111
	v_cvt_pk_bf16_f32 v98, v113, v115
	v_cvt_pk_bf16_f32 v99, v119, v121
	v_pk_add_f32 v[100:101], v[114:115], v[100:101]
	s_waitcnt lgkmcnt(6)
	v_mfma_f32_16x16x32_bf16 v[50:53], v[14:17], v[82:85], v[50:53]
	v_pk_add_f32 v[100:101], v[118:119], v[100:101]
	v_pk_add_f32 v[100:101], v[120:121], v[100:101]
	s_waitcnt lgkmcnt(4)
	v_mfma_f32_16x16x32_bf16 v[54:57], v[10:13], v[82:85], v[54:57]
	v_fma_f32 v88, v88, v122, v100
	v_fma_f32 v89, v89, v123, v101
	s_waitcnt lgkmcnt(2)
	v_mfma_f32_16x16x32_bf16 v[58:61], v[6:9], v[82:85], v[58:61]
	s_waitcnt lgkmcnt(0)
	v_mfma_f32_16x16x32_bf16 v[62:65], v[2:5], v[82:85], v[62:65]
	v_mfma_f32_16x16x32_bf16 v[34:37], v[14:17], v[96:99], v[34:37]
	v_mfma_f32_16x16x32_bf16 v[38:41], v[10:13], v[96:99], v[38:41]
	v_mfma_f32_16x16x32_bf16 v[42:45], v[6:9], v[96:99], v[42:45]
	v_mfma_f32_16x16x32_bf16 v[46:49], v[2:5], v[96:99], v[46:49]
	s_setprio 0
	v_mov_b32_e32 v95, v117
	v_mov_b32_e32 v82, v81
	s_branch .LBB0_333

; #define LAS __attribute__((address_space(3)))
; template <int MODE> ...
;     ...
;             if (MODE == 1) { const int ks = ktok0 + 64 * t + 32 * hf;
;                 if (ks + 31 < qtok0 - 128 || ks > qtok0 + 31 + 128) continue; }
;             bf16x8 kf[2][2][2];
; #pragma unroll
;             for (int jj = 0; jj < 2; ++jj)
; #pragma unroll
;                 for (int kt = 0; kt < 2; ++kt)
; #pragma unroll
;                     for (int ks = 0; ks < 2; ++ks) kf[jj][kt][ks] = *(const LAS bf16x8*)(Sl + kad[jj][ks] + (32 * hf + 16 * kt) * 128);
;             f32x4 bb[2][2];
; #pragma unroll
;             for (int jj = 0; jj < 2; ++jj) { const LAS f32x4* bl = bcp + ((MODE == 0) ? (dr0 + t - act0) * 8 : 16 * t + 8 * hf) + bofs[jj];
; #pragma unroll
;                 for (int kt = 0; kt < 2; ++kt) bb[jj][kt] = bl[4 * kt]; }
;             s16x4 vlo[2][4], vhi[2][4];
; #pragma unroll
;             for (int jj = 0; jj < 2; ++jj)
; #pragma unroll
;                 for (int dt = 0; dt < 4; ++dt) { const LAS unsigned char* vp = Sl + vad[jj] + (32 * hf) * 128 + ((dt ^ sv) << 5);
;                     vlo[jj][dt] = __builtin_bit_cast(s16x4, __builtin_amdgcn_ds_read_tr16_b64_v4i16((LAS s16x4*)(vp)));
;                     vhi[jj][dt] = __builtin_bit_cast(s16x4, __builtin_amdgcn_ds_read_tr16_b64_v4i16((LAS s16x4*)(vp + 2048))); }
;             __builtin_amdgcn_sched_barrier(0);
;             f32x4 s[2][2];
; #pragma unroll
;             for (int jj = 0; jj < 2; ++jj)
; #pragma unroll
;                 for (int kt = 0; kt < 2; ++kt) { f32x4 a = (MODE == 0) ? bb[jj][kt] + mneg[jj][kt] : bb[jj][kt];
;                     a = __builtin_amdgcn_mfma_f32_16x16x32_bf16(kf[jj][kt][0], qf[jj][0], a, 0, 0, 0);
;                     s[jj][kt] = __builtin_amdgcn_mfma_f32_16x16x32_bf16(kf[jj][kt][1], qf[jj][1], a, 0, 0, 0); }
;             u32x4 pw[2];
; #pragma unroll
;             for (int jj = 0; jj < 2; ++jj) {
;                 const float tm = vmax3(vmax3(s[jj][0][0], s[jj][0][1], s[jj][0][2]), vmax3(s[jj][0][3], s[jj][1][0], s[jj][1][1]), vmax3(s[jj][1][2], s[jj][1][3], s[jj][1][3]));
;                 const float mn = quad_max3(mrun[jj], tm);
;                 const float alpha = __builtin_amdgcn_exp2f(mrun[jj] - mn);
;                 mrun[jj] = mn;
;                 float rsum = 0.f;
; #pragma unroll
;                 for (int kt = 0; kt < 2; ++kt)
; #pragma unroll
.LBB0_356:
	v_lshl_add_u64 v[6:7], v[66:67], 1, s[38:39]
	global_load_dwordx4 v[2:5], v[6:7], off
	global_load_dwordx4 v[10:13], v[6:7], off offset:64
	v_add_co_u32_e32 v6, vcc, 0x12000, v6
	s_cmp_lt_i32 s5, 1
	s_nop 0
	v_addc_co_u32_e32 v7, vcc, 0, v7, vcc
	global_load_dwordx4 v[14:17], v[6:7], off
	s_nop 0
	global_load_dwordx4 v[6:9], v[6:7], off offset:64
	s_cbranch_scc1 .LBB0_361
	s_mul_i32 s0, s22, 0x600
	s_add_i32 s27, s0, 0
	s_add_i32 s0, s26, s86
	s_mul_hi_i32 s14, s0, 0x55555556
	s_lshr_b32 s15, s14, 31
	s_add_i32 s14, s14, s15
	s_mul_i32 s14, s14, 3
	s_sub_i32 s0, s0, s14
	s_lshl_b32 s30, s26, 6
	s_lshl_b32 s0, s0, 14
	s_add_i32 s14, s30, s24
	s_add_i32 s27, s27, 0x10000
	s_add_i32 s0, s0, 0
	s_lshl_b32 s26, s26, 8
	s_or_b32 s15, s14, 31
	s_add_i32 s31, s25, 0xffffff80
	s_cmp_lt_i32 s15, s31
	s_cselect_b64 s[38:39], -1, 0
	s_addk_i32 s25, 0x9f
	s_cmp_gt_i32 s14, s25
	s_cselect_b64 s[40:41], -1, 0
	s_or_b64 s[38:39], s[38:39], s[40:41]
	v_add_u32_e32 v100, s0, v70
	v_add_u32_e32 v99, s0, v71
	v_add3_u32 v66, v72, v73, s0
	s_movk_i32 s0, 0x60
	s_and_b64 vcc, exec, s[38:39]
	v_add_u32_e32 v98, v66, v74
	v_xad_u32 v97, v74, 32, v66
	v_xad_u32 v0, v74, 64, v66
	v_xad_u32 v96, v74, s0, v66
	s_cbranch_vccnz .LBB0_359
	s_add_i32 s0, s27, s26
	v_lshl_add_u32 v66, v93, 4, s0
	ds_read_b128 v[102:105], v100
	ds_read_b128 v[106:109], v100 offset:2048
	ds_read_b128 v[110:113], v99
	ds_read_b128 v[118:121], v99 offset:2048
	ds_read_b128 v[122:125], v66
	ds_read_b128 v[126:129], v66 offset:64
	v_lshl_add_u32 v66, v94, 4, s0
	ds_read_b128 v[130:133], v66
	ds_read_b128 v[134:137], v66 offset:64
	ds_read_b64_tr_b16 v[78:79], v98 offset:8192
	ds_read_b64_tr_b16 v[80:81], v98 offset:10240
	ds_read_b64_tr_b16 v[74:75], v97 offset:8192
	ds_read_b64_tr_b16 v[76:77], v97 offset:10240
	ds_read_b64_tr_b16 v[70:71], v0 offset:8192
	ds_read_b64_tr_b16 v[72:73], v0 offset:10240
	ds_read_b64_tr_b16 v[66:67], v96 offset:8192
	ds_read_b64_tr_b16 v[68:69], v96 offset:10240
	s_waitcnt lgkmcnt(11)
	v_mfma_f32_16x16x32_bf16 v[122:125], v[102:105], v[30:33], v[122:125]
	s_waitcnt lgkmcnt(10)
	v_mfma_f32_16x16x32_bf16 v[126:129], v[106:109], v[30:33], v[126:129]
	s_waitcnt lgkmcnt(9)
	v_mfma_f32_16x16x32_bf16 v[102:105], v[102:105], v[22:25], v[130:133]
	s_waitcnt lgkmcnt(8)
	v_mfma_f32_16x16x32_bf16 v[106:109], v[106:109], v[22:25], v[134:137]
	v_mfma_f32_16x16x32_bf16 v[102:105], v[110:113], v[18:21], v[102:105]
	v_mfma_f32_16x16x32_bf16 v[106:109], v[118:121], v[18:21], v[106:109]
	v_mfma_f32_16x16x32_bf16 v[122:125], v[110:113], v[26:29], v[122:125]
	s_nop 5
	v_maximum3_f32 v111, v102, v103, v104
	v_maximum3_f32 v113, v105, v106, v107
	v_maximum3_f32 v115, v108, v109, v109
	v_mfma_f32_16x16x32_bf16 v[126:129], v[118:121], v[26:29], v[126:129]
	v_maximum3_f32 v111, v111, v113, v115
	v_maximum3_f32 v83, v122, v123, v124
	v_mov_b32_e32 v113, v111
	s_nop 1
	v_permlane16_swap_b32_e32 v111, v113
	v_maximum3_f32 v111, v111, v113, v113
	s_nop 0
	v_maximum3_f32 v84, v125, v126, v127
	v_maximum3_f32 v85, v128, v129, v129
	v_maximum3_f32 v83, v83, v84, v85
	v_mov_b32_e32 v84, v83
	s_nop 1
	v_permlane16_swap_b32_e32 v83, v84
	v_maximum3_f32 v83, v83, v84, v84
	v_mov_b32_e32 v113, v111
	v_mov_b32_e32 v84, v83
	s_nop 0
	v_permlane32_swap_b32_e32 v111, v113
	v_permlane32_swap_b32_e32 v83, v84
	v_maximum3_f32 v117, v95, v111, v113
	v_maximum3_f32 v101, v82, v83, v84
	v_pk_add_f32 v[200:201], v[102:103], v[116:117] op_sel:[0,1] op_sel_hi:[1,1] neg_lo:[0,1] neg_hi:[0,1]
	v_pk_add_f32 v[202:203], v[104:105], v[116:117] op_sel:[0,1] op_sel_hi:[1,1] neg_lo:[0,1] neg_hi:[0,1]
	v_pk_add_f32 v[204:205], v[106:107], v[116:117] op_sel:[0,1] op_sel_hi:[1,1] neg_lo:[0,1] neg_hi:[0,1]
	v_pk_add_f32 v[206:207], v[108:109], v[116:117] op_sel:[0,1] op_sel_hi:[1,1] neg_lo:[0,1] neg_hi:[0,1]
	v_pk_add_f32 v[208:209], v[122:123], v[100:101] op_sel:[0,1] op_sel_hi:[1,1] neg_lo:[0,1] neg_hi:[0,1]
	v_pk_add_f32 v[210:211], v[124:125], v[100:101] op_sel:[0,1] op_sel_hi:[1,1] neg_lo:[0,1] neg_hi:[0,1]
	v_pk_add_f32 v[212:213], v[126:127], v[100:101] op_sel:[0,1] op_sel_hi:[1,1] neg_lo:[0,1] neg_hi:[0,1]
	v_pk_add_f32 v[214:215], v[128:129], v[100:101] op_sel:[0,1] op_sel_hi:[1,1] neg_lo:[0,1] neg_hi:[0,1]
	v_exp_f32_e32 v111, v200
	v_exp_f32_e32 v110, v208
	v_exp_f32_e32 v113, v201
	v_exp_f32_e32 v112, v209
	v_exp_f32_e32 v115, v202
	v_exp_f32_e32 v114, v210
	v_exp_f32_e32 v119, v203
	v_exp_f32_e32 v118, v211
	v_exp_f32_e32 v121, v204
	v_sub_f32_e32 v82, v82, v101
	v_exp_f32_e32 v120, v212
	v_exp_f32_e32 v123, v205
	v_exp_f32_e32 v122, v213
	v_exp_f32_e32 v128, v82
	v_pk_add_f32 v[130:131], v[110:111], 0 op_sel_hi:[1,0]
	v_exp_f32_e32 v125, v206
	v_exp_f32_e32 v127, v207
	v_pk_add_f32 v[102:103], v[112:113], v[130:131]
	v_exp_f32_e32 v124, v214
	v_pk_add_f32 v[102:103], v[114:115], v[102:103]
	v_exp_f32_e32 v126, v215
	v_sub_f32_e32 v95, v95, v117
	v_pk_add_f32 v[102:103], v[118:119], v[102:103]
	v_pk_mul_f32 v[52:53], v[52:53], v[128:129] op_sel_hi:[1,0]
	v_pk_mul_f32 v[50:51], v[50:51], v[128:129] op_sel_hi:[1,0]
	v_pk_mul_f32 v[56:57], v[56:57], v[128:129] op_sel_hi:[1,0]
	v_pk_mul_f32 v[54:55], v[54:55], v[128:129] op_sel_hi:[1,0]
	v_pk_mul_f32 v[60:61], v[60:61], v[128:129] op_sel_hi:[1,0]
	v_pk_mul_f32 v[58:59], v[58:59], v[128:129] op_sel_hi:[1,0]
	v_pk_mul_f32 v[64:65], v[64:65], v[128:129] op_sel_hi:[1,0]
	v_pk_mul_f32 v[62:63], v[62:63], v[128:129] op_sel_hi:[1,0]
	v_exp_f32_e32 v129, v95
	v_pk_add_f32 v[102:103], v[120:121], v[102:103]
	v_cvt_pk_bf16_f32 v82, v110, v112
	v_pk_add_f32 v[102:103], v[122:123], v[102:103]
	v_cvt_pk_bf16_f32 v83, v114, v118
	v_pk_add_f32 v[102:103], v[124:125], v[102:103]
	v_cvt_pk_bf16_f32 v84, v120, v122
	v_pk_add_f32 v[102:103], v[126:127], v[102:103]
	v_cvt_pk_bf16_f32 v85, v124, v126
	v_pk_fma_f32 v[88:89], v[88:89], v[128:129], v[102:103]
	s_setprio 1
	v_mov_b32_e32 v102, v129
	v_pk_mul_f32 v[36:37], v[36:37], v[102:103] op_sel_hi:[1,0]
	v_pk_mul_f32 v[34:35], v[34:35], v[102:103] op_sel_hi:[1,0]
	v_pk_mul_f32 v[40:41], v[40:41], v[102:103] op_sel_hi:[1,0]
	v_pk_mul_f32 v[38:39], v[38:39], v[102:103] op_sel_hi:[1,0]
	v_pk_mul_f32 v[44:45], v[44:45], v[102:103] op_sel_hi:[1,0]
	v_pk_mul_f32 v[42:43], v[42:43], v[102:103] op_sel_hi:[1,0]
	v_pk_mul_f32 v[48:49], v[48:49], v[102:103] op_sel_hi:[1,0]
	v_pk_mul_f32 v[46:47], v[46:47], v[102:103] op_sel_hi:[1,0]
	v_cvt_pk_bf16_f32 v102, v111, v113
	v_cvt_pk_bf16_f32 v103, v115, v119
	v_cvt_pk_bf16_f32 v104, v121, v123
	v_cvt_pk_bf16_f32 v105, v125, v127
	s_waitcnt lgkmcnt(6)
; #define LAS __attribute__((address_space(3)))
; template <int MODE> ...
;     ...
;             if (MODE == 1) { const int ks = ktok0 + 64 * t + 32 * hf;
;                 if (ks + 31 < qtok0 - 128 || ks > qtok0 + 31 + 128) continue; }
;             bf16x8 kf[2][2][2];
; #pragma unroll
;             for (int jj = 0; jj < 2; ++jj)
; #pragma unroll
;                 for (int kt = 0; kt < 2; ++kt)
; #pragma unroll
;                     for (int ks = 0; ks < 2; ++ks) kf[jj][kt][ks] = *(const LAS bf16x8*)(Sl + kad[jj][ks] + (32 * hf + 16 * kt) * 128);
;             f32x4 bb[2][2];
; #pragma unroll
;             for (int jj = 0; jj < 2; ++jj) { const LAS f32x4* bl = bcp + ((MODE == 0) ? (dr0 + t - act0) * 8 : 16 * t + 8 * hf) + bofs[jj];
; #pragma unroll
;                 for (int kt = 0; kt < 2; ++kt) bb[jj][kt] = bl[4 * kt]; }
;             s16x4 vlo[2][4], vhi[2][4];
; #pragma unroll
;             for (int jj = 0; jj < 2; ++jj)
; #pragma unroll
;                 for (int dt = 0; dt < 4; ++dt) { const LAS unsigned char* vp = Sl + vad[jj] + (32 * hf) * 128 + ((dt ^ sv) << 5);
;                     vlo[jj][dt] = __builtin_bit_cast(s16x4, __builtin_amdgcn_ds_read_tr16_b64_v4i16((LAS s16x4*)(vp)));
;                     vhi[jj][dt] = __builtin_bit_cast(s16x4, __builtin_amdgcn_ds_read_tr16_b64_v4i16((LAS s16x4*)(vp + 2048))); }
;             __builtin_amdgcn_sched_barrier(0);
;             f32x4 s[2][2];
; #pragma unroll
;             for (int jj = 0; jj < 2; ++jj)
; #pragma unroll
;                 for (int kt = 0; kt < 2; ++kt) { f32x4 a = (MODE == 0) ? bb[jj][kt] + mneg[jj][kt] : bb[jj][kt];
;                     a = __builtin_amdgcn_mfma_f32_16x16x32_bf16(kf[jj][kt][0], qf[jj][0], a, 0, 0, 0);
;                     s[jj][kt] = __builtin_amdgcn_mfma_f32_16x16x32_bf16(kf[jj][kt][1], qf[jj][1], a, 0, 0, 0); }
;             u32x4 pw[2];
; #pragma unroll
;             for (int jj = 0; jj < 2; ++jj) {
;                 const float tm = vmax3(vmax3(s[jj][0][0], s[jj][0][1], s[jj][0][2]), vmax3(s[jj][0][3], s[jj][1][0], s[jj][1][1]), vmax3(s[jj][1][2], s[jj][1][3], s[jj][1][3]));
;                 const float mn = quad_max3(mrun[jj], tm);
;                 const float alpha = __builtin_amdgcn_exp2f(mrun[jj] - mn);
;                 mrun[jj] = mn;
;                 float rsum = 0.f;
; #pragma unroll
;                 for (int kt = 0; kt < 2; ++kt)
; #pragma unroll
	v_mfma_f32_16x16x32_bf16 v[50:53], v[78:81], v[82:85], v[50:53]
	s_waitcnt lgkmcnt(4)
	v_mfma_f32_16x16x32_bf16 v[54:57], v[74:77], v[82:85], v[54:57]
	s_waitcnt lgkmcnt(2)
	v_mfma_f32_16x16x32_bf16 v[58:61], v[70:73], v[82:85], v[58:61]
	s_waitcnt lgkmcnt(0)
	v_mfma_f32_16x16x32_bf16 v[62:65], v[66:69], v[82:85], v[62:65]
	v_mfma_f32_16x16x32_bf16 v[34:37], v[78:81], v[102:105], v[34:37]
	v_mfma_f32_16x16x32_bf16 v[38:41], v[74:77], v[102:105], v[38:41]
	v_mfma_f32_16x16x32_bf16 v[42:45], v[70:73], v[102:105], v[42:45]
	v_mfma_f32_16x16x32_bf16 v[46:49], v[66:69], v[102:105], v[46:49]
	s_setprio 0
	v_mov_b32_e32 v82, v101
	v_mov_b32_e32 v95, v117
.LBB0_359:
	s_or_b32 s0, s30, 32
	s_add_i32 s0, s0, s24
	s_or_b32 s14, s0, 31
	s_cmp_lt_i32 s14, s31
	s_cselect_b64 s[30:31], -1, 0
	s_cmp_gt_i32 s0, s25
	s_cselect_b64 s[24:25], -1, 0
	s_or_b64 s[24:25], s[30:31], s[24:25]
	s_and_b64 vcc, exec, s[24:25]
	s_cbranch_vccnz .LBB0_361
	s_add_i32 s27, s27, s26
	v_lshl_add_u32 v83, v93, 4, s27
	ds_read_b128 v[66:69], v100 offset:4096
	ds_read_b128 v[70:73], v100 offset:6144
	ds_read_b128 v[74:77], v99 offset:4096
	ds_read_b128 v[78:81], v99 offset:6144
	ds_read_b128 v[100:103], v83 offset:128
	ds_read_b128 v[104:107], v83 offset:192
	v_lshl_add_u32 v83, v94, 4, s27
	ds_read_b128 v[108:111], v83 offset:128
	ds_read_b128 v[112:115], v83 offset:192
	ds_read_b64_tr_b16 v[118:119], v98 offset:12288
	ds_read_b64_tr_b16 v[120:121], v98 offset:14336
	ds_read_b64_tr_b16 v[122:123], v97 offset:12288
	ds_read_b64_tr_b16 v[124:125], v97 offset:14336
	ds_read_b64_tr_b16 v[126:127], v0 offset:12288
	ds_read_b64_tr_b16 v[128:129], v0 offset:14336
	ds_read_b64_tr_b16 v[130:131], v96 offset:12288
	ds_read_b64_tr_b16 v[132:133], v96 offset:14336
	s_waitcnt lgkmcnt(11)
	v_mfma_f32_16x16x32_bf16 v[96:99], v[66:69], v[30:33], v[100:103]
	s_waitcnt lgkmcnt(10)
	v_mfma_f32_16x16x32_bf16 v[30:33], v[70:73], v[30:33], v[104:107]
	v_mfma_f32_16x16x32_bf16 v[96:99], v[74:77], v[26:29], v[96:99]
	v_mfma_f32_16x16x32_bf16 v[26:29], v[78:81], v[26:29], v[30:33]
	s_nop 6
	v_maximum3_f32 v0, v96, v97, v98
	v_maximum3_f32 v30, v99, v26, v27
	v_maximum3_f32 v31, v28, v29, v29
	v_maximum3_f32 v0, v0, v30, v31
	v_mov_b32_e32 v30, v0
	s_nop 1
	v_permlane16_swap_b32_e32 v0, v30
	v_maximum3_f32 v0, v0, v30, v30
	v_mov_b32_e32 v30, v0
	s_nop 1
	v_permlane32_swap_b32_e32 v0, v30
	v_maximum3_f32 v0, v82, v0, v30
	s_waitcnt lgkmcnt(9)
	v_mfma_f32_16x16x32_bf16 v[30:33], v[66:69], v[22:25], v[108:111]
	v_sub_f32_e32 v83, v82, v0
	v_sub_f32_e32 v66, v97, v0
	v_exp_f32_e32 v84, v66
	s_waitcnt lgkmcnt(8)
	v_mfma_f32_16x16x32_bf16 v[22:25], v[70:73], v[22:25], v[112:115]
	v_sub_f32_e32 v66, v98, v0
	v_sub_f32_e32 v82, v96, v0
	v_sub_f32_e32 v26, v26, v0
	v_mfma_f32_16x16x32_bf16 v[30:33], v[74:77], v[18:21], v[30:33]
	v_exp_f32_e32 v74, v66
	v_sub_f32_e32 v66, v99, v0
	v_exp_f32_e32 v82, v82
	v_mfma_f32_16x16x32_bf16 v[18:21], v[78:81], v[18:21], v[22:25]
	v_exp_f32_e32 v78, v83
	v_exp_f32_e32 v70, v66
	v_exp_f32_e32 v72, v26
	v_sub_f32_e32 v22, v27, v0
	v_exp_f32_e32 v76, v22
	v_sub_f32_e32 v22, v28, v0
	v_sub_f32_e32 v0, v29, v0
	v_exp_f32_e32 v80, v22
	v_exp_f32_e32 v94, v0
	v_pk_mul_f32 v[22:23], v[50:51], v[78:79] op_sel_hi:[1,0]
	v_maximum3_f32 v0, v30, v31, v32
	v_maximum3_f32 v50, v33, v18, v19
	v_maximum3_f32 v51, v20, v21, v21
	v_maximum3_f32 v0, v0, v50, v51
	v_mov_b32_e32 v50, v0
	s_nop 1
	v_permlane16_swap_b32_e32 v0, v50
	v_maximum3_f32 v0, v0, v50, v50
	v_mov_b32_e32 v50, v0
	s_nop 1
	v_permlane32_swap_b32_e32 v0, v50
	v_maximum3_f32 v0, v95, v0, v50
	v_sub_f32_e32 v30, v30, v0
	v_exp_f32_e32 v83, v30
	v_sub_f32_e32 v30, v31, v0
	v_exp_f32_e32 v85, v30
	v_sub_f32_e32 v30, v32, v0
	v_sub_f32_e32 v18, v18, v0
	v_exp_f32_e32 v75, v30
	v_sub_f32_e32 v30, v33, v0
	v_exp_f32_e32 v73, v18
	v_sub_f32_e32 v18, v19, v0
	v_sub_f32_e32 v50, v95, v0
	v_exp_f32_e32 v71, v30
	v_exp_f32_e32 v77, v18
	v_sub_f32_e32 v18, v20, v0
	v_pk_mul_f32 v[24:25], v[52:53], v[78:79] op_sel_hi:[1,0]
	v_pk_mul_f32 v[28:29], v[56:57], v[78:79] op_sel_hi:[1,0]
	v_pk_mul_f32 v[26:27], v[54:55], v[78:79] op_sel_hi:[1,0]
	v_pk_mul_f32 v[60:61], v[60:61], v[78:79] op_sel_hi:[1,0]
	v_pk_mul_f32 v[58:59], v[58:59], v[78:79] op_sel_hi:[1,0]
	v_pk_mul_f32 v[64:65], v[64:65], v[78:79] op_sel_hi:[1,0]
	v_pk_mul_f32 v[62:63], v[62:63], v[78:79] op_sel_hi:[1,0]
	v_exp_f32_e32 v81, v18
	v_sub_f32_e32 v0, v21, v0
	v_exp_f32_e32 v79, v50
	v_pk_add_f32 v[18:19], v[82:83], 0 op_sel_hi:[1,0]
	v_exp_f32_e32 v95, v0
	s_setprio 1
	v_pk_add_f32 v[18:19], v[84:85], v[18:19]
	v_cvt_pk_bf16_f32 v66, v82, v84
	v_pk_add_f32 v[18:19], v[74:75], v[18:19]
	v_cvt_pk_bf16_f32 v67, v74, v70
	v_pk_add_f32 v[18:19], v[70:71], v[18:19]
	v_cvt_pk_bf16_f32 v68, v72, v76
	v_cvt_pk_bf16_f32 v69, v80, v94
	v_pk_add_f32 v[18:19], v[72:73], v[18:19]
	v_mov_b32_e32 v0, v79
	s_waitcnt lgkmcnt(6)
	v_mfma_f32_16x16x32_bf16 v[50:53], v[118:121], v[66:69], v[22:25]
	v_pk_mul_f32 v[20:21], v[36:37], v[0:1] op_sel_hi:[1,0]
	s_waitcnt lgkmcnt(4)
	v_mfma_f32_16x16x32_bf16 v[54:57], v[122:125], v[66:69], v[26:29]
	v_cvt_pk_bf16_f32 v22, v83, v85
	v_cvt_pk_bf16_f32 v23, v75, v71
	v_cvt_pk_bf16_f32 v24, v73, v77
	v_pk_add_f32 v[26:27], v[76:77], v[18:19]
	v_pk_mul_f32 v[18:19], v[34:35], v[0:1] op_sel_hi:[1,0]
	v_cvt_pk_bf16_f32 v25, v81, v95
	s_waitcnt lgkmcnt(2)
	v_mfma_f32_16x16x32_bf16 v[58:61], v[126:129], v[66:69], v[58:61]
	v_pk_add_f32 v[26:27], v[80:81], v[26:27]
	v_pk_add_f32 v[26:27], v[94:95], v[26:27]
	v_mfma_f32_16x16x32_bf16 v[34:37], v[118:121], v[22:25], v[18:21]
	v_fma_f32 v88, v88, v78, v26
	v_fma_f32 v89, v89, v79, v27
	s_nop 0
	v_pk_mul_f32 v[20:21], v[40:41], v[0:1] op_sel_hi:[1,0]
	v_pk_mul_f32 v[18:19], v[38:39], v[0:1] op_sel_hi:[1,0]
	s_waitcnt lgkmcnt(0)
	v_mfma_f32_16x16x32_bf16 v[62:65], v[130:133], v[66:69], v[62:65]
	v_mfma_f32_16x16x32_bf16 v[38:41], v[122:125], v[22:25], v[18:21]
	s_setprio 0
	s_nop 2
	v_pk_mul_f32 v[20:21], v[44:45], v[0:1] op_sel_hi:[1,0]
	v_pk_mul_f32 v[18:19], v[42:43], v[0:1] op_sel_hi:[1,0]
	s_nop 1
	v_mfma_f32_16x16x32_bf16 v[42:45], v[126:129], v[22:25], v[18:21]
	s_nop 2
	v_pk_mul_f32 v[20:21], v[48:49], v[0:1] op_sel_hi:[1,0]
	v_pk_mul_f32 v[18:19], v[46:47], v[0:1] op_sel_hi:[1,0]
	s_nop 1
	v_mfma_f32_16x16x32_bf16 v[46:49], v[130:133], v[22:25], v[18:21]
